# select refinement: candidates held in registers, need-th largest key by 21-step bitwise search with wave popcounts, emission by mbcnt compaction (no LDS histograms / per-key atomics)
# speedup vs baseline: 1.0549x; 1.0175x over previous
.LBB0_875:
	v_cndmask_b32_e64 v3, 0, 1, s[14:15]
	s_and_b64 vcc, exec, s[16:17]
	v_cmp_ne_u32_e64 s[4:5], 1, v3
	s_cbranch_vccz .LBB0_907
	s_and_b64 vcc, exec, s[4:5]
	s_cbranch_vccnz .LBB0_907
	s_lshl_b32 s57, s53, 5
	s_add_i32 s92, s57, 0x25800
	v_mov_b32_e32 v232, s92
	ds_read2_b32 v[234:235], v232 offset0:1 offset1:5
	ds_read2_b32 v[236:237], v232 offset0:0 offset1:2
	s_lshl_b32 s89, s53, 11
	s_lshl_b32 s90, s53, 10
	v_lshl_add_u32 v238, v145, 2, s89
	v_lshl_add_u32 v245, v145, 1, s90
	v_add_u32_e32 v238, 0x20000, v238
	v_add_u32_e32 v245, 0x22000, v245
	s_lshl_b32 s60, s53, 9
	s_add_i32 s60, s60, 0x24000
	v_mov_b32_e32 v246, s60
	s_add_i32 s60, s90, 0x24800
	v_mov_b32_e32 v244, s60
	s_waitcnt lgkmcnt(0)
	v_readfirstlane_b32 s91, v234
	v_readfirstlane_b32 s93, v235
	v_readfirstlane_b32 s33, v236
	v_readfirstlane_b32 s90, v237
	s_lshl_b32 s33, s33, 21
	s_add_i32 s60, s93, 63
	s_lshr_b32 s60, s60, 6
	s_cmp_le_u32 s60, 2
	s_cbranch_scc1 .Lref_v2
	s_cmp_le_u32 s60, 4
	s_cbranch_scc1 .Lref_v4
.Lref_v8:
	ds_read_b32 v216, v238
	ds_read_u16 v224, v245
	ds_read_b32 v217, v238 offset:256
	ds_read_u16 v225, v245 offset:128
	ds_read_b32 v218, v238 offset:512
	ds_read_u16 v226, v245 offset:256
	ds_read_b32 v219, v238 offset:768
	ds_read_u16 v227, v245 offset:384
	ds_read_b32 v220, v238 offset:1024
	ds_read_u16 v228, v245 offset:512
	ds_read_b32 v221, v238 offset:1280
	ds_read_u16 v229, v245 offset:640
	ds_read_b32 v222, v238 offset:1536
	ds_read_u16 v230, v245 offset:768
	ds_read_b32 v223, v238 offset:1792
	ds_read_u16 v231, v245 offset:896
	v_cmp_gt_u32_e64 s[8:9], s93, v145
	v_add_u32_e32 v241, 64, v145
	v_cmp_gt_u32_e64 s[12:13], s93, v241
	v_add_u32_e32 v241, 128, v145
	v_cmp_gt_u32_e64 s[14:15], s93, v241
	v_add_u32_e32 v241, 192, v145
	v_cmp_gt_u32_e64 s[16:17], s93, v241
	v_add_u32_e32 v241, 256, v145
	v_cmp_gt_u32_e64 s[18:19], s93, v241
	v_add_u32_e32 v241, 320, v145
	v_cmp_gt_u32_e64 s[22:23], s93, v241
	v_add_u32_e32 v241, 384, v145
	v_cmp_gt_u32_e64 s[24:25], s93, v241
	v_add_u32_e32 v241, 448, v145
	v_cmp_gt_u32_e64 s[58:59], s93, v241
	s_waitcnt lgkmcnt(0)
	v_cndmask_b32_e64 v216, 0, v216, s[8:9]
	v_cndmask_b32_e64 v217, 0, v217, s[12:13]
	v_cndmask_b32_e64 v218, 0, v218, s[14:15]
	v_cndmask_b32_e64 v219, 0, v219, s[16:17]
	v_cndmask_b32_e64 v220, 0, v220, s[18:19]
	v_cndmask_b32_e64 v221, 0, v221, s[22:23]
	v_cndmask_b32_e64 v222, 0, v222, s[24:25]
	v_cndmask_b32_e64 v223, 0, v223, s[58:59]
	s_or_b32 s57, s33, 0x100000
	v_cmp_ge_u32_e64 s[8:9], v216, s57
	v_cmp_ge_u32_e64 s[12:13], v217, s57
	v_cmp_ge_u32_e64 s[14:15], v218, s57
	v_cmp_ge_u32_e64 s[16:17], v219, s57
	v_cmp_ge_u32_e64 s[18:19], v220, s57
	v_cmp_ge_u32_e64 s[22:23], v221, s57
	v_cmp_ge_u32_e64 s[24:25], v222, s57
	v_cmp_ge_u32_e64 s[58:59], v223, s57
	s_bcnt1_i32_b64 s89, s[8:9]
	s_bcnt1_i32_b64 s61, s[12:13]
	s_add_u32 s89, s89, s61
	s_bcnt1_i32_b64 s61, s[14:15]
	s_add_u32 s89, s89, s61
	s_bcnt1_i32_b64 s61, s[16:17]
	s_add_u32 s89, s89, s61
	s_bcnt1_i32_b64 s61, s[18:19]
	s_add_u32 s89, s89, s61
	s_bcnt1_i32_b64 s61, s[22:23]
	s_add_u32 s89, s89, s61
	s_bcnt1_i32_b64 s61, s[24:25]
	s_add_u32 s89, s89, s61
	s_bcnt1_i32_b64 s61, s[58:59]
	s_add_u32 s89, s89, s61
	s_cmp_ge_u32 s89, s91
	s_cselect_b32 s33, s57, s33
	s_or_b32 s57, s33, 0x80000
	v_cmp_ge_u32_e64 s[8:9], v216, s57
	v_cmp_ge_u32_e64 s[12:13], v217, s57
	v_cmp_ge_u32_e64 s[14:15], v218, s57
	v_cmp_ge_u32_e64 s[16:17], v219, s57
	v_cmp_ge_u32_e64 s[18:19], v220, s57
	v_cmp_ge_u32_e64 s[22:23], v221, s57
	v_cmp_ge_u32_e64 s[24:25], v222, s57
	v_cmp_ge_u32_e64 s[58:59], v223, s57
	s_bcnt1_i32_b64 s89, s[8:9]
	s_bcnt1_i32_b64 s61, s[12:13]
	s_add_u32 s89, s89, s61
	s_bcnt1_i32_b64 s61, s[14:15]
	s_add_u32 s89, s89, s61
	s_bcnt1_i32_b64 s61, s[16:17]
	s_add_u32 s89, s89, s61
	s_bcnt1_i32_b64 s61, s[18:19]
	s_add_u32 s89, s89, s61
	s_bcnt1_i32_b64 s61, s[22:23]
	s_add_u32 s89, s89, s61
	s_bcnt1_i32_b64 s61, s[24:25]
	s_add_u32 s89, s89, s61
	s_bcnt1_i32_b64 s61, s[58:59]
	s_add_u32 s89, s89, s61
	s_cmp_ge_u32 s89, s91
	s_cselect_b32 s33, s57, s33
	s_or_b32 s57, s33, 0x40000
	v_cmp_ge_u32_e64 s[8:9], v216, s57
	v_cmp_ge_u32_e64 s[12:13], v217, s57
	v_cmp_ge_u32_e64 s[14:15], v218, s57
	v_cmp_ge_u32_e64 s[16:17], v219, s57
	v_cmp_ge_u32_e64 s[18:19], v220, s57
	v_cmp_ge_u32_e64 s[22:23], v221, s57
	v_cmp_ge_u32_e64 s[24:25], v222, s57
	v_cmp_ge_u32_e64 s[58:59], v223, s57
	s_bcnt1_i32_b64 s89, s[8:9]
	s_bcnt1_i32_b64 s61, s[12:13]
	s_add_u32 s89, s89, s61
	s_bcnt1_i32_b64 s61, s[14:15]
	s_add_u32 s89, s89, s61
	s_bcnt1_i32_b64 s61, s[16:17]
	s_add_u32 s89, s89, s61
	s_bcnt1_i32_b64 s61, s[18:19]
	s_add_u32 s89, s89, s61
	s_bcnt1_i32_b64 s61, s[22:23]
	s_add_u32 s89, s89, s61
	s_bcnt1_i32_b64 s61, s[24:25]
	s_add_u32 s89, s89, s61
	s_bcnt1_i32_b64 s61, s[58:59]
	s_add_u32 s89, s89, s61
	s_cmp_ge_u32 s89, s91
	s_cselect_b32 s33, s57, s33
	s_or_b32 s57, s33, 0x20000
	v_cmp_ge_u32_e64 s[8:9], v216, s57
	v_cmp_ge_u32_e64 s[12:13], v217, s57
	v_cmp_ge_u32_e64 s[14:15], v218, s57
	v_cmp_ge_u32_e64 s[16:17], v219, s57
	v_cmp_ge_u32_e64 s[18:19], v220, s57
	v_cmp_ge_u32_e64 s[22:23], v221, s57
	v_cmp_ge_u32_e64 s[24:25], v222, s57
	v_cmp_ge_u32_e64 s[58:59], v223, s57
	s_bcnt1_i32_b64 s89, s[8:9]
	s_bcnt1_i32_b64 s61, s[12:13]
	s_add_u32 s89, s89, s61
	s_bcnt1_i32_b64 s61, s[14:15]
	s_add_u32 s89, s89, s61
	s_bcnt1_i32_b64 s61, s[16:17]
	s_add_u32 s89, s89, s61
	s_bcnt1_i32_b64 s61, s[18:19]
	s_add_u32 s89, s89, s61
	s_bcnt1_i32_b64 s61, s[22:23]
	s_add_u32 s89, s89, s61
	s_bcnt1_i32_b64 s61, s[24:25]
	s_add_u32 s89, s89, s61
	s_bcnt1_i32_b64 s61, s[58:59]
	s_add_u32 s89, s89, s61
	s_cmp_ge_u32 s89, s91
	s_cselect_b32 s33, s57, s33
	s_or_b32 s57, s33, 0x10000
	v_cmp_ge_u32_e64 s[8:9], v216, s57
	v_cmp_ge_u32_e64 s[12:13], v217, s57
	v_cmp_ge_u32_e64 s[14:15], v218, s57
	v_cmp_ge_u32_e64 s[16:17], v219, s57
	v_cmp_ge_u32_e64 s[18:19], v220, s57
	v_cmp_ge_u32_e64 s[22:23], v221, s57
	v_cmp_ge_u32_e64 s[24:25], v222, s57
	v_cmp_ge_u32_e64 s[58:59], v223, s57
	s_bcnt1_i32_b64 s89, s[8:9]
	s_bcnt1_i32_b64 s61, s[12:13]
	s_add_u32 s89, s89, s61
	s_bcnt1_i32_b64 s61, s[14:15]
	s_add_u32 s89, s89, s61
	s_bcnt1_i32_b64 s61, s[16:17]
	s_add_u32 s89, s89, s61
	s_bcnt1_i32_b64 s61, s[18:19]
	s_add_u32 s89, s89, s61
	s_bcnt1_i32_b64 s61, s[22:23]
	s_add_u32 s89, s89, s61
	s_bcnt1_i32_b64 s61, s[24:25]
	s_add_u32 s89, s89, s61
	s_bcnt1_i32_b64 s61, s[58:59]
	s_add_u32 s89, s89, s61
	s_cmp_ge_u32 s89, s91
	s_cselect_b32 s33, s57, s33
	s_or_b32 s57, s33, 0x8000
	v_cmp_ge_u32_e64 s[8:9], v216, s57
	v_cmp_ge_u32_e64 s[12:13], v217, s57
	v_cmp_ge_u32_e64 s[14:15], v218, s57
	v_cmp_ge_u32_e64 s[16:17], v219, s57
	v_cmp_ge_u32_e64 s[18:19], v220, s57
	v_cmp_ge_u32_e64 s[22:23], v221, s57
	v_cmp_ge_u32_e64 s[24:25], v222, s57
	v_cmp_ge_u32_e64 s[58:59], v223, s57
	s_bcnt1_i32_b64 s89, s[8:9]
	s_bcnt1_i32_b64 s61, s[12:13]
	s_add_u32 s89, s89, s61
	s_bcnt1_i32_b64 s61, s[14:15]
	s_add_u32 s89, s89, s61
	s_bcnt1_i32_b64 s61, s[16:17]
	s_add_u32 s89, s89, s61
	s_bcnt1_i32_b64 s61, s[18:19]
	s_add_u32 s89, s89, s61
	s_bcnt1_i32_b64 s61, s[22:23]
	s_add_u32 s89, s89, s61
	s_bcnt1_i32_b64 s61, s[24:25]
	s_add_u32 s89, s89, s61
	s_bcnt1_i32_b64 s61, s[58:59]
	s_add_u32 s89, s89, s61
	s_cmp_ge_u32 s89, s91
	s_cselect_b32 s33, s57, s33
	s_or_b32 s57, s33, 0x4000
	v_cmp_ge_u32_e64 s[8:9], v216, s57
	v_cmp_ge_u32_e64 s[12:13], v217, s57
	v_cmp_ge_u32_e64 s[14:15], v218, s57
	v_cmp_ge_u32_e64 s[16:17], v219, s57
	v_cmp_ge_u32_e64 s[18:19], v220, s57
	v_cmp_ge_u32_e64 s[22:23], v221, s57
	v_cmp_ge_u32_e64 s[24:25], v222, s57
	v_cmp_ge_u32_e64 s[58:59], v223, s57
	s_bcnt1_i32_b64 s89, s[8:9]
	s_bcnt1_i32_b64 s61, s[12:13]
	s_add_u32 s89, s89, s61
	s_bcnt1_i32_b64 s61, s[14:15]
	s_add_u32 s89, s89, s61
	s_bcnt1_i32_b64 s61, s[16:17]
	s_add_u32 s89, s89, s61
	s_bcnt1_i32_b64 s61, s[18:19]
	s_add_u32 s89, s89, s61
	s_bcnt1_i32_b64 s61, s[22:23]
	s_add_u32 s89, s89, s61
	s_bcnt1_i32_b64 s61, s[24:25]
	s_add_u32 s89, s89, s61
	s_bcnt1_i32_b64 s61, s[58:59]
	s_add_u32 s89, s89, s61
	s_cmp_ge_u32 s89, s91
	s_cselect_b32 s33, s57, s33
	s_or_b32 s57, s33, 0x2000
	v_cmp_ge_u32_e64 s[8:9], v216, s57
	v_cmp_ge_u32_e64 s[12:13], v217, s57
	v_cmp_ge_u32_e64 s[14:15], v218, s57
	v_cmp_ge_u32_e64 s[16:17], v219, s57
	v_cmp_ge_u32_e64 s[18:19], v220, s57
	v_cmp_ge_u32_e64 s[22:23], v221, s57
	v_cmp_ge_u32_e64 s[24:25], v222, s57
	v_cmp_ge_u32_e64 s[58:59], v223, s57
	s_bcnt1_i32_b64 s89, s[8:9]
	s_bcnt1_i32_b64 s61, s[12:13]
	s_add_u32 s89, s89, s61
	s_bcnt1_i32_b64 s61, s[14:15]
	s_add_u32 s89, s89, s61
	s_bcnt1_i32_b64 s61, s[16:17]
	s_add_u32 s89, s89, s61
	s_bcnt1_i32_b64 s61, s[18:19]
	s_add_u32 s89, s89, s61
	s_bcnt1_i32_b64 s61, s[22:23]
	s_add_u32 s89, s89, s61
	s_bcnt1_i32_b64 s61, s[24:25]
	s_add_u32 s89, s89, s61
	s_bcnt1_i32_b64 s61, s[58:59]
	s_add_u32 s89, s89, s61
	s_cmp_ge_u32 s89, s91
	s_cselect_b32 s33, s57, s33
	s_or_b32 s57, s33, 0x1000
	v_cmp_ge_u32_e64 s[8:9], v216, s57
	v_cmp_ge_u32_e64 s[12:13], v217, s57
	v_cmp_ge_u32_e64 s[14:15], v218, s57
	v_cmp_ge_u32_e64 s[16:17], v219, s57
	v_cmp_ge_u32_e64 s[18:19], v220, s57
	v_cmp_ge_u32_e64 s[22:23], v221, s57
	v_cmp_ge_u32_e64 s[24:25], v222, s57
	v_cmp_ge_u32_e64 s[58:59], v223, s57
	s_bcnt1_i32_b64 s89, s[8:9]
	s_bcnt1_i32_b64 s61, s[12:13]
	s_add_u32 s89, s89, s61
	s_bcnt1_i32_b64 s61, s[14:15]
	s_add_u32 s89, s89, s61
	s_bcnt1_i32_b64 s61, s[16:17]
	s_add_u32 s89, s89, s61
	s_bcnt1_i32_b64 s61, s[18:19]
	s_add_u32 s89, s89, s61
	s_bcnt1_i32_b64 s61, s[22:23]
	s_add_u32 s89, s89, s61
	s_bcnt1_i32_b64 s61, s[24:25]
	s_add_u32 s89, s89, s61
	s_bcnt1_i32_b64 s61, s[58:59]
	s_add_u32 s89, s89, s61
	s_cmp_ge_u32 s89, s91
	s_cselect_b32 s33, s57, s33
	s_or_b32 s57, s33, 0x800
	v_cmp_ge_u32_e64 s[8:9], v216, s57
	v_cmp_ge_u32_e64 s[12:13], v217, s57
	v_cmp_ge_u32_e64 s[14:15], v218, s57
	v_cmp_ge_u32_e64 s[16:17], v219, s57
	v_cmp_ge_u32_e64 s[18:19], v220, s57
	v_cmp_ge_u32_e64 s[22:23], v221, s57
	v_cmp_ge_u32_e64 s[24:25], v222, s57
	v_cmp_ge_u32_e64 s[58:59], v223, s57
	s_bcnt1_i32_b64 s89, s[8:9]
	s_bcnt1_i32_b64 s61, s[12:13]
	s_add_u32 s89, s89, s61
	s_bcnt1_i32_b64 s61, s[14:15]
	s_add_u32 s89, s89, s61
	s_bcnt1_i32_b64 s61, s[16:17]
	s_add_u32 s89, s89, s61
	s_bcnt1_i32_b64 s61, s[18:19]
	s_add_u32 s89, s89, s61
	s_bcnt1_i32_b64 s61, s[22:23]
	s_add_u32 s89, s89, s61
	s_bcnt1_i32_b64 s61, s[24:25]
	s_add_u32 s89, s89, s61
	s_bcnt1_i32_b64 s61, s[58:59]
	s_add_u32 s89, s89, s61
	s_cmp_ge_u32 s89, s91
	s_cselect_b32 s33, s57, s33
	s_or_b32 s57, s33, 0x400
	v_cmp_ge_u32_e64 s[8:9], v216, s57
	v_cmp_ge_u32_e64 s[12:13], v217, s57
	v_cmp_ge_u32_e64 s[14:15], v218, s57
	v_cmp_ge_u32_e64 s[16:17], v219, s57
	v_cmp_ge_u32_e64 s[18:19], v220, s57
	v_cmp_ge_u32_e64 s[22:23], v221, s57
	v_cmp_ge_u32_e64 s[24:25], v222, s57
	v_cmp_ge_u32_e64 s[58:59], v223, s57
	s_bcnt1_i32_b64 s89, s[8:9]
	s_bcnt1_i32_b64 s61, s[12:13]
	s_add_u32 s89, s89, s61
	s_bcnt1_i32_b64 s61, s[14:15]
	s_add_u32 s89, s89, s61
	s_bcnt1_i32_b64 s61, s[16:17]
	s_add_u32 s89, s89, s61
	s_bcnt1_i32_b64 s61, s[18:19]
	s_add_u32 s89, s89, s61
	s_bcnt1_i32_b64 s61, s[22:23]
	s_add_u32 s89, s89, s61
	s_bcnt1_i32_b64 s61, s[24:25]
	s_add_u32 s89, s89, s61
	s_bcnt1_i32_b64 s61, s[58:59]
	s_add_u32 s89, s89, s61
	s_cmp_ge_u32 s89, s91
	s_cselect_b32 s33, s57, s33
	s_or_b32 s57, s33, 0x200
	v_cmp_ge_u32_e64 s[8:9], v216, s57
	v_cmp_ge_u32_e64 s[12:13], v217, s57
	v_cmp_ge_u32_e64 s[14:15], v218, s57
	v_cmp_ge_u32_e64 s[16:17], v219, s57
	v_cmp_ge_u32_e64 s[18:19], v220, s57
	v_cmp_ge_u32_e64 s[22:23], v221, s57
	v_cmp_ge_u32_e64 s[24:25], v222, s57
	v_cmp_ge_u32_e64 s[58:59], v223, s57
	s_bcnt1_i32_b64 s89, s[8:9]
	s_bcnt1_i32_b64 s61, s[12:13]
	s_add_u32 s89, s89, s61
	s_bcnt1_i32_b64 s61, s[14:15]
	s_add_u32 s89, s89, s61
	s_bcnt1_i32_b64 s61, s[16:17]
	s_add_u32 s89, s89, s61
	s_bcnt1_i32_b64 s61, s[18:19]
	s_add_u32 s89, s89, s61
	s_bcnt1_i32_b64 s61, s[22:23]
	s_add_u32 s89, s89, s61
	s_bcnt1_i32_b64 s61, s[24:25]
	s_add_u32 s89, s89, s61
	s_bcnt1_i32_b64 s61, s[58:59]
	s_add_u32 s89, s89, s61
	s_cmp_ge_u32 s89, s91
	s_cselect_b32 s33, s57, s33
	s_or_b32 s57, s33, 0x100
	v_cmp_ge_u32_e64 s[8:9], v216, s57
	v_cmp_ge_u32_e64 s[12:13], v217, s57
	v_cmp_ge_u32_e64 s[14:15], v218, s57
	v_cmp_ge_u32_e64 s[16:17], v219, s57
	v_cmp_ge_u32_e64 s[18:19], v220, s57
	v_cmp_ge_u32_e64 s[22:23], v221, s57
	v_cmp_ge_u32_e64 s[24:25], v222, s57
	v_cmp_ge_u32_e64 s[58:59], v223, s57
	s_bcnt1_i32_b64 s89, s[8:9]
	s_bcnt1_i32_b64 s61, s[12:13]
	s_add_u32 s89, s89, s61
	s_bcnt1_i32_b64 s61, s[14:15]
	s_add_u32 s89, s89, s61
	s_bcnt1_i32_b64 s61, s[16:17]
	s_add_u32 s89, s89, s61
	s_bcnt1_i32_b64 s61, s[18:19]
	s_add_u32 s89, s89, s61
	s_bcnt1_i32_b64 s61, s[22:23]
	s_add_u32 s89, s89, s61
	s_bcnt1_i32_b64 s61, s[24:25]
	s_add_u32 s89, s89, s61
	s_bcnt1_i32_b64 s61, s[58:59]
	s_add_u32 s89, s89, s61
	s_cmp_ge_u32 s89, s91
	s_cselect_b32 s33, s57, s33
	s_or_b32 s57, s33, 0x80
	v_cmp_ge_u32_e64 s[8:9], v216, s57
	v_cmp_ge_u32_e64 s[12:13], v217, s57
	v_cmp_ge_u32_e64 s[14:15], v218, s57
	v_cmp_ge_u32_e64 s[16:17], v219, s57
	v_cmp_ge_u32_e64 s[18:19], v220, s57
	v_cmp_ge_u32_e64 s[22:23], v221, s57
	v_cmp_ge_u32_e64 s[24:25], v222, s57
	v_cmp_ge_u32_e64 s[58:59], v223, s57
	s_bcnt1_i32_b64 s89, s[8:9]
	s_bcnt1_i32_b64 s61, s[12:13]
	s_add_u32 s89, s89, s61
	s_bcnt1_i32_b64 s61, s[14:15]
	s_add_u32 s89, s89, s61
	s_bcnt1_i32_b64 s61, s[16:17]
	s_add_u32 s89, s89, s61
	s_bcnt1_i32_b64 s61, s[18:19]
	s_add_u32 s89, s89, s61
	s_bcnt1_i32_b64 s61, s[22:23]
	s_add_u32 s89, s89, s61
	s_bcnt1_i32_b64 s61, s[24:25]
	s_add_u32 s89, s89, s61
	s_bcnt1_i32_b64 s61, s[58:59]
	s_add_u32 s89, s89, s61
	s_cmp_ge_u32 s89, s91
	s_cselect_b32 s33, s57, s33
	s_or_b32 s57, s33, 0x40
	v_cmp_ge_u32_e64 s[8:9], v216, s57
	v_cmp_ge_u32_e64 s[12:13], v217, s57
	v_cmp_ge_u32_e64 s[14:15], v218, s57
	v_cmp_ge_u32_e64 s[16:17], v219, s57
	v_cmp_ge_u32_e64 s[18:19], v220, s57
	v_cmp_ge_u32_e64 s[22:23], v221, s57
	v_cmp_ge_u32_e64 s[24:25], v222, s57
	v_cmp_ge_u32_e64 s[58:59], v223, s57
	s_bcnt1_i32_b64 s89, s[8:9]
	s_bcnt1_i32_b64 s61, s[12:13]
	s_add_u32 s89, s89, s61
	s_bcnt1_i32_b64 s61, s[14:15]
	s_add_u32 s89, s89, s61
	s_bcnt1_i32_b64 s61, s[16:17]
	s_add_u32 s89, s89, s61
	s_bcnt1_i32_b64 s61, s[18:19]
	s_add_u32 s89, s89, s61
	s_bcnt1_i32_b64 s61, s[22:23]
	s_add_u32 s89, s89, s61
	s_bcnt1_i32_b64 s61, s[24:25]
	s_add_u32 s89, s89, s61
	s_bcnt1_i32_b64 s61, s[58:59]
	s_add_u32 s89, s89, s61
	s_cmp_ge_u32 s89, s91
	s_cselect_b32 s33, s57, s33
	s_or_b32 s57, s33, 0x20
	v_cmp_ge_u32_e64 s[8:9], v216, s57
	v_cmp_ge_u32_e64 s[12:13], v217, s57
	v_cmp_ge_u32_e64 s[14:15], v218, s57
	v_cmp_ge_u32_e64 s[16:17], v219, s57
	v_cmp_ge_u32_e64 s[18:19], v220, s57
	v_cmp_ge_u32_e64 s[22:23], v221, s57
	v_cmp_ge_u32_e64 s[24:25], v222, s57
	v_cmp_ge_u32_e64 s[58:59], v223, s57
	s_bcnt1_i32_b64 s89, s[8:9]
	s_bcnt1_i32_b64 s61, s[12:13]
	s_add_u32 s89, s89, s61
	s_bcnt1_i32_b64 s61, s[14:15]
	s_add_u32 s89, s89, s61
	s_bcnt1_i32_b64 s61, s[16:17]
	s_add_u32 s89, s89, s61
	s_bcnt1_i32_b64 s61, s[18:19]
	s_add_u32 s89, s89, s61
	s_bcnt1_i32_b64 s61, s[22:23]
	s_add_u32 s89, s89, s61
	s_bcnt1_i32_b64 s61, s[24:25]
	s_add_u32 s89, s89, s61
	s_bcnt1_i32_b64 s61, s[58:59]
	s_add_u32 s89, s89, s61
	s_cmp_ge_u32 s89, s91
	s_cselect_b32 s33, s57, s33
	s_or_b32 s57, s33, 0x10
	v_cmp_ge_u32_e64 s[8:9], v216, s57
	v_cmp_ge_u32_e64 s[12:13], v217, s57
	v_cmp_ge_u32_e64 s[14:15], v218, s57
	v_cmp_ge_u32_e64 s[16:17], v219, s57
	v_cmp_ge_u32_e64 s[18:19], v220, s57
	v_cmp_ge_u32_e64 s[22:23], v221, s57
	v_cmp_ge_u32_e64 s[24:25], v222, s57
	v_cmp_ge_u32_e64 s[58:59], v223, s57
	s_bcnt1_i32_b64 s89, s[8:9]
	s_bcnt1_i32_b64 s61, s[12:13]
	s_add_u32 s89, s89, s61
	s_bcnt1_i32_b64 s61, s[14:15]
	s_add_u32 s89, s89, s61
	s_bcnt1_i32_b64 s61, s[16:17]
	s_add_u32 s89, s89, s61
	s_bcnt1_i32_b64 s61, s[18:19]
	s_add_u32 s89, s89, s61
	s_bcnt1_i32_b64 s61, s[22:23]
	s_add_u32 s89, s89, s61
	s_bcnt1_i32_b64 s61, s[24:25]
	s_add_u32 s89, s89, s61
	s_bcnt1_i32_b64 s61, s[58:59]
	s_add_u32 s89, s89, s61
	s_cmp_ge_u32 s89, s91
	s_cselect_b32 s33, s57, s33
	s_or_b32 s57, s33, 0x8
	v_cmp_ge_u32_e64 s[8:9], v216, s57
	v_cmp_ge_u32_e64 s[12:13], v217, s57
	v_cmp_ge_u32_e64 s[14:15], v218, s57
	v_cmp_ge_u32_e64 s[16:17], v219, s57
	v_cmp_ge_u32_e64 s[18:19], v220, s57
	v_cmp_ge_u32_e64 s[22:23], v221, s57
	v_cmp_ge_u32_e64 s[24:25], v222, s57
	v_cmp_ge_u32_e64 s[58:59], v223, s57
	s_bcnt1_i32_b64 s89, s[8:9]
	s_bcnt1_i32_b64 s61, s[12:13]
	s_add_u32 s89, s89, s61
	s_bcnt1_i32_b64 s61, s[14:15]
	s_add_u32 s89, s89, s61
	s_bcnt1_i32_b64 s61, s[16:17]
	s_add_u32 s89, s89, s61
	s_bcnt1_i32_b64 s61, s[18:19]
	s_add_u32 s89, s89, s61
	s_bcnt1_i32_b64 s61, s[22:23]
	s_add_u32 s89, s89, s61
	s_bcnt1_i32_b64 s61, s[24:25]
	s_add_u32 s89, s89, s61
	s_bcnt1_i32_b64 s61, s[58:59]
	s_add_u32 s89, s89, s61
	s_cmp_ge_u32 s89, s91
	s_cselect_b32 s33, s57, s33
	s_or_b32 s57, s33, 0x4
	v_cmp_ge_u32_e64 s[8:9], v216, s57
	v_cmp_ge_u32_e64 s[12:13], v217, s57
	v_cmp_ge_u32_e64 s[14:15], v218, s57
	v_cmp_ge_u32_e64 s[16:17], v219, s57
	v_cmp_ge_u32_e64 s[18:19], v220, s57
	v_cmp_ge_u32_e64 s[22:23], v221, s57
	v_cmp_ge_u32_e64 s[24:25], v222, s57
	v_cmp_ge_u32_e64 s[58:59], v223, s57
	s_bcnt1_i32_b64 s89, s[8:9]
	s_bcnt1_i32_b64 s61, s[12:13]
	s_add_u32 s89, s89, s61
	s_bcnt1_i32_b64 s61, s[14:15]
	s_add_u32 s89, s89, s61
	s_bcnt1_i32_b64 s61, s[16:17]
	s_add_u32 s89, s89, s61
	s_bcnt1_i32_b64 s61, s[18:19]
	s_add_u32 s89, s89, s61
	s_bcnt1_i32_b64 s61, s[22:23]
	s_add_u32 s89, s89, s61
	s_bcnt1_i32_b64 s61, s[24:25]
	s_add_u32 s89, s89, s61
	s_bcnt1_i32_b64 s61, s[58:59]
	s_add_u32 s89, s89, s61
	s_cmp_ge_u32 s89, s91
	s_cselect_b32 s33, s57, s33
	s_or_b32 s57, s33, 0x2
	v_cmp_ge_u32_e64 s[8:9], v216, s57
	v_cmp_ge_u32_e64 s[12:13], v217, s57
	v_cmp_ge_u32_e64 s[14:15], v218, s57
	v_cmp_ge_u32_e64 s[16:17], v219, s57
	v_cmp_ge_u32_e64 s[18:19], v220, s57
	v_cmp_ge_u32_e64 s[22:23], v221, s57
	v_cmp_ge_u32_e64 s[24:25], v222, s57
	v_cmp_ge_u32_e64 s[58:59], v223, s57
	s_bcnt1_i32_b64 s89, s[8:9]
	s_bcnt1_i32_b64 s61, s[12:13]
	s_add_u32 s89, s89, s61
	s_bcnt1_i32_b64 s61, s[14:15]
	s_add_u32 s89, s89, s61
	s_bcnt1_i32_b64 s61, s[16:17]
	s_add_u32 s89, s89, s61
	s_bcnt1_i32_b64 s61, s[18:19]
	s_add_u32 s89, s89, s61
	s_bcnt1_i32_b64 s61, s[22:23]
	s_add_u32 s89, s89, s61
	s_bcnt1_i32_b64 s61, s[24:25]
	s_add_u32 s89, s89, s61
	s_bcnt1_i32_b64 s61, s[58:59]
	s_add_u32 s89, s89, s61
	s_cmp_ge_u32 s89, s91
	s_cselect_b32 s33, s57, s33
	s_or_b32 s57, s33, 0x1
	v_cmp_ge_u32_e64 s[8:9], v216, s57
	v_cmp_ge_u32_e64 s[12:13], v217, s57
	v_cmp_ge_u32_e64 s[14:15], v218, s57
	v_cmp_ge_u32_e64 s[16:17], v219, s57
	v_cmp_ge_u32_e64 s[18:19], v220, s57
	v_cmp_ge_u32_e64 s[22:23], v221, s57
	v_cmp_ge_u32_e64 s[24:25], v222, s57
	v_cmp_ge_u32_e64 s[58:59], v223, s57
	s_bcnt1_i32_b64 s89, s[8:9]
	s_bcnt1_i32_b64 s61, s[12:13]
	s_add_u32 s89, s89, s61
	s_bcnt1_i32_b64 s61, s[14:15]
	s_add_u32 s89, s89, s61
	s_bcnt1_i32_b64 s61, s[16:17]
	s_add_u32 s89, s89, s61
	s_bcnt1_i32_b64 s61, s[18:19]
	s_add_u32 s89, s89, s61
	s_bcnt1_i32_b64 s61, s[22:23]
	s_add_u32 s89, s89, s61
	s_bcnt1_i32_b64 s61, s[24:25]
	s_add_u32 s89, s89, s61
	s_bcnt1_i32_b64 s61, s[58:59]
	s_add_u32 s89, s89, s61
	s_cmp_ge_u32 s89, s91
	s_cselect_b32 s33, s57, s33
	v_cmp_gt_u32_e64 s[8:9], v216, s33
	v_cmp_gt_u32_e64 s[12:13], v217, s33
	v_cmp_gt_u32_e64 s[14:15], v218, s33
	v_cmp_gt_u32_e64 s[16:17], v219, s33
	v_cmp_gt_u32_e64 s[18:19], v220, s33
	v_cmp_gt_u32_e64 s[22:23], v221, s33
	v_cmp_gt_u32_e64 s[24:25], v222, s33
	v_cmp_gt_u32_e64 s[58:59], v223, s33
	s_bcnt1_i32_b64 s89, s[8:9]
	s_bcnt1_i32_b64 s61, s[12:13]
	s_add_u32 s89, s89, s61
	s_bcnt1_i32_b64 s61, s[14:15]
	s_add_u32 s89, s89, s61
	s_bcnt1_i32_b64 s61, s[16:17]
	s_add_u32 s89, s89, s61
	s_bcnt1_i32_b64 s61, s[18:19]
	s_add_u32 s89, s89, s61
	s_bcnt1_i32_b64 s61, s[22:23]
	s_add_u32 s89, s89, s61
	s_bcnt1_i32_b64 s61, s[24:25]
	s_add_u32 s89, s89, s61
	s_bcnt1_i32_b64 s61, s[58:59]
	s_add_u32 s89, s89, s61
	s_sub_u32 s91, s91, s89
	v_cmp_eq_u32_e64 s[8:9], v216, s33
	v_cmp_eq_u32_e64 s[12:13], v217, s33
	v_cmp_eq_u32_e64 s[14:15], v218, s33
	v_cmp_eq_u32_e64 s[16:17], v219, s33
	v_cmp_eq_u32_e64 s[18:19], v220, s33
	v_cmp_eq_u32_e64 s[22:23], v221, s33
	v_cmp_eq_u32_e64 s[24:25], v222, s33
	v_cmp_eq_u32_e64 s[58:59], v223, s33
	s_bcnt1_i32_b64 s89, s[8:9]
	s_bcnt1_i32_b64 s61, s[12:13]
	s_add_u32 s89, s89, s61
	s_bcnt1_i32_b64 s61, s[14:15]
	s_add_u32 s89, s89, s61
	s_bcnt1_i32_b64 s61, s[16:17]
	s_add_u32 s89, s89, s61
	s_bcnt1_i32_b64 s61, s[18:19]
	s_add_u32 s89, s89, s61
	s_bcnt1_i32_b64 s61, s[22:23]
	s_add_u32 s89, s89, s61
	s_bcnt1_i32_b64 s61, s[24:25]
	s_add_u32 s89, s89, s61
	s_bcnt1_i32_b64 s61, s[58:59]
	s_add_u32 s89, s89, s61
	s_add_u32 s57, s33, 1
	s_cmp_eq_u32 s91, s89
	s_cselect_b32 s57, s33, s57
	s_cselect_b32 s60, 1, 0
	v_cmp_ge_u32_e64 s[8:9], v216, s57
	v_cmp_ge_u32_e64 s[12:13], v217, s57
	v_cmp_ge_u32_e64 s[14:15], v218, s57
	v_cmp_ge_u32_e64 s[16:17], v219, s57
	v_cmp_ge_u32_e64 s[18:19], v220, s57
	v_cmp_ge_u32_e64 s[22:23], v221, s57
	v_cmp_ge_u32_e64 s[24:25], v222, s57
	v_cmp_ge_u32_e64 s[58:59], v223, s57
	s_nop 1
	v_mbcnt_lo_u32_b32 v241, s8, 0
	v_mbcnt_hi_u32_b32 v241, s9, v241
	v_add_u32_e32 v241, s90, v241
	v_and_b32_e32 v241, 0xff, v241
	v_lshl_add_u32 v241, v241, 1, v246
	s_mov_b64 exec, s[8:9]
	ds_write_b16 v241, v224
	s_mov_b64 exec, -1
	s_bcnt1_i32_b64 s61, s[8:9]
	s_add_u32 s90, s90, s61
	v_mbcnt_lo_u32_b32 v241, s12, 0
	v_mbcnt_hi_u32_b32 v241, s13, v241
	v_add_u32_e32 v241, s90, v241
	v_and_b32_e32 v241, 0xff, v241
	v_lshl_add_u32 v241, v241, 1, v246
	s_mov_b64 exec, s[12:13]
	ds_write_b16 v241, v225
	s_mov_b64 exec, -1
	s_bcnt1_i32_b64 s61, s[12:13]
	s_add_u32 s90, s90, s61
	v_mbcnt_lo_u32_b32 v241, s14, 0
	v_mbcnt_hi_u32_b32 v241, s15, v241
	v_add_u32_e32 v241, s90, v241
	v_and_b32_e32 v241, 0xff, v241
	v_lshl_add_u32 v241, v241, 1, v246
	s_mov_b64 exec, s[14:15]
	ds_write_b16 v241, v226
	s_mov_b64 exec, -1
	s_bcnt1_i32_b64 s61, s[14:15]
	s_add_u32 s90, s90, s61
	v_mbcnt_lo_u32_b32 v241, s16, 0
	v_mbcnt_hi_u32_b32 v241, s17, v241
	v_add_u32_e32 v241, s90, v241
	v_and_b32_e32 v241, 0xff, v241
	v_lshl_add_u32 v241, v241, 1, v246
	s_mov_b64 exec, s[16:17]
	ds_write_b16 v241, v227
	s_mov_b64 exec, -1
	s_bcnt1_i32_b64 s61, s[16:17]
	s_add_u32 s90, s90, s61
	v_mbcnt_lo_u32_b32 v241, s18, 0
	v_mbcnt_hi_u32_b32 v241, s19, v241
	v_add_u32_e32 v241, s90, v241
	v_and_b32_e32 v241, 0xff, v241
	v_lshl_add_u32 v241, v241, 1, v246
	s_mov_b64 exec, s[18:19]
	ds_write_b16 v241, v228
	s_mov_b64 exec, -1
	s_bcnt1_i32_b64 s61, s[18:19]
	s_add_u32 s90, s90, s61
	v_mbcnt_lo_u32_b32 v241, s22, 0
	v_mbcnt_hi_u32_b32 v241, s23, v241
	v_add_u32_e32 v241, s90, v241
	v_and_b32_e32 v241, 0xff, v241
	v_lshl_add_u32 v241, v241, 1, v246
	s_mov_b64 exec, s[22:23]
	ds_write_b16 v241, v229
	s_mov_b64 exec, -1
	s_bcnt1_i32_b64 s61, s[22:23]
	s_add_u32 s90, s90, s61
	v_mbcnt_lo_u32_b32 v241, s24, 0
	v_mbcnt_hi_u32_b32 v241, s25, v241
	v_add_u32_e32 v241, s90, v241
	v_and_b32_e32 v241, 0xff, v241
	v_lshl_add_u32 v241, v241, 1, v246
	s_mov_b64 exec, s[24:25]
	ds_write_b16 v241, v230
	s_mov_b64 exec, -1
	s_bcnt1_i32_b64 s61, s[24:25]
	s_add_u32 s90, s90, s61
	v_mbcnt_lo_u32_b32 v241, s58, 0
	v_mbcnt_hi_u32_b32 v241, s59, v241
	v_add_u32_e32 v241, s90, v241
	v_and_b32_e32 v241, 0xff, v241
	v_lshl_add_u32 v241, v241, 1, v246
	s_mov_b64 exec, s[58:59]
	ds_write_b16 v241, v231
	s_mov_b64 exec, -1
	s_bcnt1_i32_b64 s61, s[58:59]
	s_add_u32 s90, s90, s61
	s_mov_b32 s92, 0
	s_cmp_lg_u32 s60, 0
	s_cbranch_scc1 .Lref_fin
	v_cmp_eq_u32_e64 s[8:9], v216, s33
	v_cmp_eq_u32_e64 s[12:13], v217, s33
	v_cmp_eq_u32_e64 s[14:15], v218, s33
	v_cmp_eq_u32_e64 s[16:17], v219, s33
	v_cmp_eq_u32_e64 s[18:19], v220, s33
	v_cmp_eq_u32_e64 s[22:23], v221, s33
	v_cmp_eq_u32_e64 s[24:25], v222, s33
	v_cmp_eq_u32_e64 s[58:59], v223, s33
	s_nop 1
	v_mbcnt_lo_u32_b32 v241, s8, 0
	v_mbcnt_hi_u32_b32 v241, s9, v241
	v_add_u32_e32 v241, s92, v241
	v_lshl_add_u32 v241, v241, 1, v244
	s_mov_b64 exec, s[8:9]
	ds_write_b16 v241, v224
	s_mov_b64 exec, -1
	s_bcnt1_i32_b64 s61, s[8:9]
	s_add_u32 s92, s92, s61
	v_mbcnt_lo_u32_b32 v241, s12, 0
	v_mbcnt_hi_u32_b32 v241, s13, v241
	v_add_u32_e32 v241, s92, v241
	v_lshl_add_u32 v241, v241, 1, v244
	s_mov_b64 exec, s[12:13]
	ds_write_b16 v241, v225
	s_mov_b64 exec, -1
	s_bcnt1_i32_b64 s61, s[12:13]
	s_add_u32 s92, s92, s61
	v_mbcnt_lo_u32_b32 v241, s14, 0
	v_mbcnt_hi_u32_b32 v241, s15, v241
	v_add_u32_e32 v241, s92, v241
	v_lshl_add_u32 v241, v241, 1, v244
	s_mov_b64 exec, s[14:15]
	ds_write_b16 v241, v226
	s_mov_b64 exec, -1
	s_bcnt1_i32_b64 s61, s[14:15]
	s_add_u32 s92, s92, s61
	v_mbcnt_lo_u32_b32 v241, s16, 0
	v_mbcnt_hi_u32_b32 v241, s17, v241
	v_add_u32_e32 v241, s92, v241
	v_lshl_add_u32 v241, v241, 1, v244
	s_mov_b64 exec, s[16:17]
	ds_write_b16 v241, v227
	s_mov_b64 exec, -1
	s_bcnt1_i32_b64 s61, s[16:17]
	s_add_u32 s92, s92, s61
	v_mbcnt_lo_u32_b32 v241, s18, 0
	v_mbcnt_hi_u32_b32 v241, s19, v241
	v_add_u32_e32 v241, s92, v241
	v_lshl_add_u32 v241, v241, 1, v244
	s_mov_b64 exec, s[18:19]
	ds_write_b16 v241, v228
	s_mov_b64 exec, -1
	s_bcnt1_i32_b64 s61, s[18:19]
	s_add_u32 s92, s92, s61
	v_mbcnt_lo_u32_b32 v241, s22, 0
	v_mbcnt_hi_u32_b32 v241, s23, v241
	v_add_u32_e32 v241, s92, v241
	v_lshl_add_u32 v241, v241, 1, v244
	s_mov_b64 exec, s[22:23]
	ds_write_b16 v241, v229
	s_mov_b64 exec, -1
	s_bcnt1_i32_b64 s61, s[22:23]
	s_add_u32 s92, s92, s61
	v_mbcnt_lo_u32_b32 v241, s24, 0
	v_mbcnt_hi_u32_b32 v241, s25, v241
	v_add_u32_e32 v241, s92, v241
	v_lshl_add_u32 v241, v241, 1, v244
	s_mov_b64 exec, s[24:25]
	ds_write_b16 v241, v230
	s_mov_b64 exec, -1
	s_bcnt1_i32_b64 s61, s[24:25]
	s_add_u32 s92, s92, s61
	v_mbcnt_lo_u32_b32 v241, s58, 0
	v_mbcnt_hi_u32_b32 v241, s59, v241
	v_add_u32_e32 v241, s92, v241
	v_lshl_add_u32 v241, v241, 1, v244
	s_mov_b64 exec, s[58:59]
	ds_write_b16 v241, v231
	s_mov_b64 exec, -1
	s_bcnt1_i32_b64 s61, s[58:59]
	s_add_u32 s92, s92, s61
	s_branch .Lref_fin
.Lref_v4:
	ds_read_b32 v216, v238
	ds_read_u16 v224, v245
	ds_read_b32 v217, v238 offset:256
	ds_read_u16 v225, v245 offset:128
	ds_read_b32 v218, v238 offset:512
	ds_read_u16 v226, v245 offset:256
	ds_read_b32 v219, v238 offset:768
	ds_read_u16 v227, v245 offset:384
	v_cmp_gt_u32_e64 s[8:9], s93, v145
	v_add_u32_e32 v241, 64, v145
	v_cmp_gt_u32_e64 s[12:13], s93, v241
	v_add_u32_e32 v241, 128, v145
	v_cmp_gt_u32_e64 s[14:15], s93, v241
	v_add_u32_e32 v241, 192, v145
	v_cmp_gt_u32_e64 s[16:17], s93, v241
	s_waitcnt lgkmcnt(0)
	v_cndmask_b32_e64 v216, 0, v216, s[8:9]
	v_cndmask_b32_e64 v217, 0, v217, s[12:13]
	v_cndmask_b32_e64 v218, 0, v218, s[14:15]
	v_cndmask_b32_e64 v219, 0, v219, s[16:17]
	s_or_b32 s57, s33, 0x100000
	v_cmp_ge_u32_e64 s[8:9], v216, s57
	v_cmp_ge_u32_e64 s[12:13], v217, s57
	v_cmp_ge_u32_e64 s[14:15], v218, s57
	v_cmp_ge_u32_e64 s[16:17], v219, s57
	s_bcnt1_i32_b64 s89, s[8:9]
	s_bcnt1_i32_b64 s61, s[12:13]
	s_add_u32 s89, s89, s61
	s_bcnt1_i32_b64 s61, s[14:15]
	s_add_u32 s89, s89, s61
	s_bcnt1_i32_b64 s61, s[16:17]
	s_add_u32 s89, s89, s61
	s_cmp_ge_u32 s89, s91
	s_cselect_b32 s33, s57, s33
	s_or_b32 s57, s33, 0x80000
	v_cmp_ge_u32_e64 s[8:9], v216, s57
	v_cmp_ge_u32_e64 s[12:13], v217, s57
	v_cmp_ge_u32_e64 s[14:15], v218, s57
	v_cmp_ge_u32_e64 s[16:17], v219, s57
	s_bcnt1_i32_b64 s89, s[8:9]
	s_bcnt1_i32_b64 s61, s[12:13]
	s_add_u32 s89, s89, s61
	s_bcnt1_i32_b64 s61, s[14:15]
	s_add_u32 s89, s89, s61
	s_bcnt1_i32_b64 s61, s[16:17]
	s_add_u32 s89, s89, s61
	s_cmp_ge_u32 s89, s91
	s_cselect_b32 s33, s57, s33
	s_or_b32 s57, s33, 0x40000
	v_cmp_ge_u32_e64 s[8:9], v216, s57
	v_cmp_ge_u32_e64 s[12:13], v217, s57
	v_cmp_ge_u32_e64 s[14:15], v218, s57
	v_cmp_ge_u32_e64 s[16:17], v219, s57
	s_bcnt1_i32_b64 s89, s[8:9]
	s_bcnt1_i32_b64 s61, s[12:13]
	s_add_u32 s89, s89, s61
	s_bcnt1_i32_b64 s61, s[14:15]
	s_add_u32 s89, s89, s61
	s_bcnt1_i32_b64 s61, s[16:17]
	s_add_u32 s89, s89, s61
	s_cmp_ge_u32 s89, s91
	s_cselect_b32 s33, s57, s33
	s_or_b32 s57, s33, 0x20000
	v_cmp_ge_u32_e64 s[8:9], v216, s57
	v_cmp_ge_u32_e64 s[12:13], v217, s57
	v_cmp_ge_u32_e64 s[14:15], v218, s57
	v_cmp_ge_u32_e64 s[16:17], v219, s57
	s_bcnt1_i32_b64 s89, s[8:9]
	s_bcnt1_i32_b64 s61, s[12:13]
	s_add_u32 s89, s89, s61
	s_bcnt1_i32_b64 s61, s[14:15]
	s_add_u32 s89, s89, s61
	s_bcnt1_i32_b64 s61, s[16:17]
	s_add_u32 s89, s89, s61
	s_cmp_ge_u32 s89, s91
	s_cselect_b32 s33, s57, s33
	s_or_b32 s57, s33, 0x10000
	v_cmp_ge_u32_e64 s[8:9], v216, s57
	v_cmp_ge_u32_e64 s[12:13], v217, s57
	v_cmp_ge_u32_e64 s[14:15], v218, s57
	v_cmp_ge_u32_e64 s[16:17], v219, s57
	s_bcnt1_i32_b64 s89, s[8:9]
	s_bcnt1_i32_b64 s61, s[12:13]
	s_add_u32 s89, s89, s61
	s_bcnt1_i32_b64 s61, s[14:15]
	s_add_u32 s89, s89, s61
	s_bcnt1_i32_b64 s61, s[16:17]
	s_add_u32 s89, s89, s61
	s_cmp_ge_u32 s89, s91
	s_cselect_b32 s33, s57, s33
	s_or_b32 s57, s33, 0x8000
	v_cmp_ge_u32_e64 s[8:9], v216, s57
	v_cmp_ge_u32_e64 s[12:13], v217, s57
	v_cmp_ge_u32_e64 s[14:15], v218, s57
	v_cmp_ge_u32_e64 s[16:17], v219, s57
	s_bcnt1_i32_b64 s89, s[8:9]
	s_bcnt1_i32_b64 s61, s[12:13]
	s_add_u32 s89, s89, s61
	s_bcnt1_i32_b64 s61, s[14:15]
	s_add_u32 s89, s89, s61
	s_bcnt1_i32_b64 s61, s[16:17]
	s_add_u32 s89, s89, s61
	s_cmp_ge_u32 s89, s91
	s_cselect_b32 s33, s57, s33
	s_or_b32 s57, s33, 0x4000
	v_cmp_ge_u32_e64 s[8:9], v216, s57
	v_cmp_ge_u32_e64 s[12:13], v217, s57
	v_cmp_ge_u32_e64 s[14:15], v218, s57
	v_cmp_ge_u32_e64 s[16:17], v219, s57
	s_bcnt1_i32_b64 s89, s[8:9]
	s_bcnt1_i32_b64 s61, s[12:13]
	s_add_u32 s89, s89, s61
	s_bcnt1_i32_b64 s61, s[14:15]
	s_add_u32 s89, s89, s61
	s_bcnt1_i32_b64 s61, s[16:17]
	s_add_u32 s89, s89, s61
	s_cmp_ge_u32 s89, s91
	s_cselect_b32 s33, s57, s33
	s_or_b32 s57, s33, 0x2000
	v_cmp_ge_u32_e64 s[8:9], v216, s57
	v_cmp_ge_u32_e64 s[12:13], v217, s57
	v_cmp_ge_u32_e64 s[14:15], v218, s57
	v_cmp_ge_u32_e64 s[16:17], v219, s57
	s_bcnt1_i32_b64 s89, s[8:9]
	s_bcnt1_i32_b64 s61, s[12:13]
	s_add_u32 s89, s89, s61
	s_bcnt1_i32_b64 s61, s[14:15]
	s_add_u32 s89, s89, s61
	s_bcnt1_i32_b64 s61, s[16:17]
	s_add_u32 s89, s89, s61
	s_cmp_ge_u32 s89, s91
	s_cselect_b32 s33, s57, s33
	s_or_b32 s57, s33, 0x1000
	v_cmp_ge_u32_e64 s[8:9], v216, s57
	v_cmp_ge_u32_e64 s[12:13], v217, s57
	v_cmp_ge_u32_e64 s[14:15], v218, s57
	v_cmp_ge_u32_e64 s[16:17], v219, s57
	s_bcnt1_i32_b64 s89, s[8:9]
	s_bcnt1_i32_b64 s61, s[12:13]
	s_add_u32 s89, s89, s61
	s_bcnt1_i32_b64 s61, s[14:15]
	s_add_u32 s89, s89, s61
	s_bcnt1_i32_b64 s61, s[16:17]
	s_add_u32 s89, s89, s61
	s_cmp_ge_u32 s89, s91
	s_cselect_b32 s33, s57, s33
	s_or_b32 s57, s33, 0x800
	v_cmp_ge_u32_e64 s[8:9], v216, s57
	v_cmp_ge_u32_e64 s[12:13], v217, s57
	v_cmp_ge_u32_e64 s[14:15], v218, s57
	v_cmp_ge_u32_e64 s[16:17], v219, s57
	s_bcnt1_i32_b64 s89, s[8:9]
	s_bcnt1_i32_b64 s61, s[12:13]
	s_add_u32 s89, s89, s61
	s_bcnt1_i32_b64 s61, s[14:15]
	s_add_u32 s89, s89, s61
	s_bcnt1_i32_b64 s61, s[16:17]
	s_add_u32 s89, s89, s61
	s_cmp_ge_u32 s89, s91
	s_cselect_b32 s33, s57, s33
	s_or_b32 s57, s33, 0x400
	v_cmp_ge_u32_e64 s[8:9], v216, s57
	v_cmp_ge_u32_e64 s[12:13], v217, s57
	v_cmp_ge_u32_e64 s[14:15], v218, s57
	v_cmp_ge_u32_e64 s[16:17], v219, s57
	s_bcnt1_i32_b64 s89, s[8:9]
	s_bcnt1_i32_b64 s61, s[12:13]
	s_add_u32 s89, s89, s61
	s_bcnt1_i32_b64 s61, s[14:15]
	s_add_u32 s89, s89, s61
	s_bcnt1_i32_b64 s61, s[16:17]
	s_add_u32 s89, s89, s61
	s_cmp_ge_u32 s89, s91
	s_cselect_b32 s33, s57, s33
	s_or_b32 s57, s33, 0x200
	v_cmp_ge_u32_e64 s[8:9], v216, s57
	v_cmp_ge_u32_e64 s[12:13], v217, s57
	v_cmp_ge_u32_e64 s[14:15], v218, s57
	v_cmp_ge_u32_e64 s[16:17], v219, s57
	s_bcnt1_i32_b64 s89, s[8:9]
	s_bcnt1_i32_b64 s61, s[12:13]
	s_add_u32 s89, s89, s61
	s_bcnt1_i32_b64 s61, s[14:15]
	s_add_u32 s89, s89, s61
	s_bcnt1_i32_b64 s61, s[16:17]
	s_add_u32 s89, s89, s61
	s_cmp_ge_u32 s89, s91
	s_cselect_b32 s33, s57, s33
	s_or_b32 s57, s33, 0x100
	v_cmp_ge_u32_e64 s[8:9], v216, s57
	v_cmp_ge_u32_e64 s[12:13], v217, s57
	v_cmp_ge_u32_e64 s[14:15], v218, s57
	v_cmp_ge_u32_e64 s[16:17], v219, s57
	s_bcnt1_i32_b64 s89, s[8:9]
	s_bcnt1_i32_b64 s61, s[12:13]
	s_add_u32 s89, s89, s61
	s_bcnt1_i32_b64 s61, s[14:15]
	s_add_u32 s89, s89, s61
	s_bcnt1_i32_b64 s61, s[16:17]
	s_add_u32 s89, s89, s61
	s_cmp_ge_u32 s89, s91
	s_cselect_b32 s33, s57, s33
	s_or_b32 s57, s33, 0x80
	v_cmp_ge_u32_e64 s[8:9], v216, s57
	v_cmp_ge_u32_e64 s[12:13], v217, s57
	v_cmp_ge_u32_e64 s[14:15], v218, s57
	v_cmp_ge_u32_e64 s[16:17], v219, s57
	s_bcnt1_i32_b64 s89, s[8:9]
	s_bcnt1_i32_b64 s61, s[12:13]
	s_add_u32 s89, s89, s61
	s_bcnt1_i32_b64 s61, s[14:15]
	s_add_u32 s89, s89, s61
	s_bcnt1_i32_b64 s61, s[16:17]
	s_add_u32 s89, s89, s61
	s_cmp_ge_u32 s89, s91
	s_cselect_b32 s33, s57, s33
	s_or_b32 s57, s33, 0x40
	v_cmp_ge_u32_e64 s[8:9], v216, s57
	v_cmp_ge_u32_e64 s[12:13], v217, s57
	v_cmp_ge_u32_e64 s[14:15], v218, s57
	v_cmp_ge_u32_e64 s[16:17], v219, s57
	s_bcnt1_i32_b64 s89, s[8:9]
	s_bcnt1_i32_b64 s61, s[12:13]
	s_add_u32 s89, s89, s61
	s_bcnt1_i32_b64 s61, s[14:15]
	s_add_u32 s89, s89, s61
	s_bcnt1_i32_b64 s61, s[16:17]
	s_add_u32 s89, s89, s61
	s_cmp_ge_u32 s89, s91
	s_cselect_b32 s33, s57, s33
	s_or_b32 s57, s33, 0x20
	v_cmp_ge_u32_e64 s[8:9], v216, s57
	v_cmp_ge_u32_e64 s[12:13], v217, s57
	v_cmp_ge_u32_e64 s[14:15], v218, s57
	v_cmp_ge_u32_e64 s[16:17], v219, s57
	s_bcnt1_i32_b64 s89, s[8:9]
	s_bcnt1_i32_b64 s61, s[12:13]
	s_add_u32 s89, s89, s61
	s_bcnt1_i32_b64 s61, s[14:15]
	s_add_u32 s89, s89, s61
	s_bcnt1_i32_b64 s61, s[16:17]
	s_add_u32 s89, s89, s61
	s_cmp_ge_u32 s89, s91
	s_cselect_b32 s33, s57, s33
	s_or_b32 s57, s33, 0x10
	v_cmp_ge_u32_e64 s[8:9], v216, s57
	v_cmp_ge_u32_e64 s[12:13], v217, s57
	v_cmp_ge_u32_e64 s[14:15], v218, s57
	v_cmp_ge_u32_e64 s[16:17], v219, s57
	s_bcnt1_i32_b64 s89, s[8:9]
	s_bcnt1_i32_b64 s61, s[12:13]
	s_add_u32 s89, s89, s61
	s_bcnt1_i32_b64 s61, s[14:15]
	s_add_u32 s89, s89, s61
	s_bcnt1_i32_b64 s61, s[16:17]
	s_add_u32 s89, s89, s61
	s_cmp_ge_u32 s89, s91
	s_cselect_b32 s33, s57, s33
	s_or_b32 s57, s33, 0x8
	v_cmp_ge_u32_e64 s[8:9], v216, s57
	v_cmp_ge_u32_e64 s[12:13], v217, s57
	v_cmp_ge_u32_e64 s[14:15], v218, s57
	v_cmp_ge_u32_e64 s[16:17], v219, s57
	s_bcnt1_i32_b64 s89, s[8:9]
	s_bcnt1_i32_b64 s61, s[12:13]
	s_add_u32 s89, s89, s61
	s_bcnt1_i32_b64 s61, s[14:15]
	s_add_u32 s89, s89, s61
	s_bcnt1_i32_b64 s61, s[16:17]
	s_add_u32 s89, s89, s61
	s_cmp_ge_u32 s89, s91
	s_cselect_b32 s33, s57, s33
	s_or_b32 s57, s33, 0x4
	v_cmp_ge_u32_e64 s[8:9], v216, s57
	v_cmp_ge_u32_e64 s[12:13], v217, s57
	v_cmp_ge_u32_e64 s[14:15], v218, s57
	v_cmp_ge_u32_e64 s[16:17], v219, s57
	s_bcnt1_i32_b64 s89, s[8:9]
	s_bcnt1_i32_b64 s61, s[12:13]
	s_add_u32 s89, s89, s61
	s_bcnt1_i32_b64 s61, s[14:15]
	s_add_u32 s89, s89, s61
	s_bcnt1_i32_b64 s61, s[16:17]
	s_add_u32 s89, s89, s61
	s_cmp_ge_u32 s89, s91
	s_cselect_b32 s33, s57, s33
	s_or_b32 s57, s33, 0x2
	v_cmp_ge_u32_e64 s[8:9], v216, s57
	v_cmp_ge_u32_e64 s[12:13], v217, s57
	v_cmp_ge_u32_e64 s[14:15], v218, s57
	v_cmp_ge_u32_e64 s[16:17], v219, s57
	s_bcnt1_i32_b64 s89, s[8:9]
	s_bcnt1_i32_b64 s61, s[12:13]
	s_add_u32 s89, s89, s61
	s_bcnt1_i32_b64 s61, s[14:15]
	s_add_u32 s89, s89, s61
	s_bcnt1_i32_b64 s61, s[16:17]
	s_add_u32 s89, s89, s61
	s_cmp_ge_u32 s89, s91
	s_cselect_b32 s33, s57, s33
	s_or_b32 s57, s33, 0x1
	v_cmp_ge_u32_e64 s[8:9], v216, s57
	v_cmp_ge_u32_e64 s[12:13], v217, s57
	v_cmp_ge_u32_e64 s[14:15], v218, s57
	v_cmp_ge_u32_e64 s[16:17], v219, s57
	s_bcnt1_i32_b64 s89, s[8:9]
	s_bcnt1_i32_b64 s61, s[12:13]
	s_add_u32 s89, s89, s61
	s_bcnt1_i32_b64 s61, s[14:15]
	s_add_u32 s89, s89, s61
	s_bcnt1_i32_b64 s61, s[16:17]
	s_add_u32 s89, s89, s61
	s_cmp_ge_u32 s89, s91
	s_cselect_b32 s33, s57, s33
	v_cmp_gt_u32_e64 s[8:9], v216, s33
	v_cmp_gt_u32_e64 s[12:13], v217, s33
	v_cmp_gt_u32_e64 s[14:15], v218, s33
	v_cmp_gt_u32_e64 s[16:17], v219, s33
	s_bcnt1_i32_b64 s89, s[8:9]
	s_bcnt1_i32_b64 s61, s[12:13]
	s_add_u32 s89, s89, s61
	s_bcnt1_i32_b64 s61, s[14:15]
	s_add_u32 s89, s89, s61
	s_bcnt1_i32_b64 s61, s[16:17]
	s_add_u32 s89, s89, s61
	s_sub_u32 s91, s91, s89
	v_cmp_eq_u32_e64 s[8:9], v216, s33
	v_cmp_eq_u32_e64 s[12:13], v217, s33
	v_cmp_eq_u32_e64 s[14:15], v218, s33
	v_cmp_eq_u32_e64 s[16:17], v219, s33
	s_bcnt1_i32_b64 s89, s[8:9]
	s_bcnt1_i32_b64 s61, s[12:13]
	s_add_u32 s89, s89, s61
	s_bcnt1_i32_b64 s61, s[14:15]
	s_add_u32 s89, s89, s61
	s_bcnt1_i32_b64 s61, s[16:17]
	s_add_u32 s89, s89, s61
	s_add_u32 s57, s33, 1
	s_cmp_eq_u32 s91, s89
	s_cselect_b32 s57, s33, s57
	s_cselect_b32 s60, 1, 0
	v_cmp_ge_u32_e64 s[8:9], v216, s57
	v_cmp_ge_u32_e64 s[12:13], v217, s57
	v_cmp_ge_u32_e64 s[14:15], v218, s57
	v_cmp_ge_u32_e64 s[16:17], v219, s57
	s_nop 1
	v_mbcnt_lo_u32_b32 v241, s8, 0
	v_mbcnt_hi_u32_b32 v241, s9, v241
	v_add_u32_e32 v241, s90, v241
	v_and_b32_e32 v241, 0xff, v241
	v_lshl_add_u32 v241, v241, 1, v246
	s_mov_b64 exec, s[8:9]
	ds_write_b16 v241, v224
	s_mov_b64 exec, -1
	s_bcnt1_i32_b64 s61, s[8:9]
	s_add_u32 s90, s90, s61
	v_mbcnt_lo_u32_b32 v241, s12, 0
	v_mbcnt_hi_u32_b32 v241, s13, v241
	v_add_u32_e32 v241, s90, v241
	v_and_b32_e32 v241, 0xff, v241
	v_lshl_add_u32 v241, v241, 1, v246
	s_mov_b64 exec, s[12:13]
	ds_write_b16 v241, v225
	s_mov_b64 exec, -1
	s_bcnt1_i32_b64 s61, s[12:13]
	s_add_u32 s90, s90, s61
	v_mbcnt_lo_u32_b32 v241, s14, 0
	v_mbcnt_hi_u32_b32 v241, s15, v241
	v_add_u32_e32 v241, s90, v241
	v_and_b32_e32 v241, 0xff, v241
	v_lshl_add_u32 v241, v241, 1, v246
	s_mov_b64 exec, s[14:15]
	ds_write_b16 v241, v226
	s_mov_b64 exec, -1
	s_bcnt1_i32_b64 s61, s[14:15]
	s_add_u32 s90, s90, s61
	v_mbcnt_lo_u32_b32 v241, s16, 0
	v_mbcnt_hi_u32_b32 v241, s17, v241
	v_add_u32_e32 v241, s90, v241
	v_and_b32_e32 v241, 0xff, v241
	v_lshl_add_u32 v241, v241, 1, v246
	s_mov_b64 exec, s[16:17]
	ds_write_b16 v241, v227
	s_mov_b64 exec, -1
	s_bcnt1_i32_b64 s61, s[16:17]
	s_add_u32 s90, s90, s61
	s_mov_b32 s92, 0
	s_cmp_lg_u32 s60, 0
	s_cbranch_scc1 .Lref_fin
	v_cmp_eq_u32_e64 s[8:9], v216, s33
	v_cmp_eq_u32_e64 s[12:13], v217, s33
	v_cmp_eq_u32_e64 s[14:15], v218, s33
	v_cmp_eq_u32_e64 s[16:17], v219, s33
	s_nop 1
	v_mbcnt_lo_u32_b32 v241, s8, 0
	v_mbcnt_hi_u32_b32 v241, s9, v241
	v_add_u32_e32 v241, s92, v241
	v_lshl_add_u32 v241, v241, 1, v244
	s_mov_b64 exec, s[8:9]
	ds_write_b16 v241, v224
	s_mov_b64 exec, -1
	s_bcnt1_i32_b64 s61, s[8:9]
	s_add_u32 s92, s92, s61
	v_mbcnt_lo_u32_b32 v241, s12, 0
	v_mbcnt_hi_u32_b32 v241, s13, v241
	v_add_u32_e32 v241, s92, v241
	v_lshl_add_u32 v241, v241, 1, v244
	s_mov_b64 exec, s[12:13]
	ds_write_b16 v241, v225
	s_mov_b64 exec, -1
	s_bcnt1_i32_b64 s61, s[12:13]
	s_add_u32 s92, s92, s61
	v_mbcnt_lo_u32_b32 v241, s14, 0
	v_mbcnt_hi_u32_b32 v241, s15, v241
	v_add_u32_e32 v241, s92, v241
	v_lshl_add_u32 v241, v241, 1, v244
	s_mov_b64 exec, s[14:15]
	ds_write_b16 v241, v226
	s_mov_b64 exec, -1
	s_bcnt1_i32_b64 s61, s[14:15]
	s_add_u32 s92, s92, s61
	v_mbcnt_lo_u32_b32 v241, s16, 0
	v_mbcnt_hi_u32_b32 v241, s17, v241
	v_add_u32_e32 v241, s92, v241
	v_lshl_add_u32 v241, v241, 1, v244
	s_mov_b64 exec, s[16:17]
	ds_write_b16 v241, v227
	s_mov_b64 exec, -1
	s_bcnt1_i32_b64 s61, s[16:17]
	s_add_u32 s92, s92, s61
	s_branch .Lref_fin
.Lref_v2:
	ds_read_b32 v216, v238
	ds_read_u16 v224, v245
	ds_read_b32 v217, v238 offset:256
	ds_read_u16 v225, v245 offset:128
	v_cmp_gt_u32_e64 s[8:9], s93, v145
	v_add_u32_e32 v241, 64, v145
	v_cmp_gt_u32_e64 s[12:13], s93, v241
	s_waitcnt lgkmcnt(0)
	v_cndmask_b32_e64 v216, 0, v216, s[8:9]
	v_cndmask_b32_e64 v217, 0, v217, s[12:13]
	s_or_b32 s57, s33, 0x100000
	v_cmp_ge_u32_e64 s[8:9], v216, s57
	v_cmp_ge_u32_e64 s[12:13], v217, s57
	s_bcnt1_i32_b64 s89, s[8:9]
	s_bcnt1_i32_b64 s61, s[12:13]
	s_add_u32 s89, s89, s61
	s_cmp_ge_u32 s89, s91
	s_cselect_b32 s33, s57, s33
	s_or_b32 s57, s33, 0x80000
	v_cmp_ge_u32_e64 s[8:9], v216, s57
	v_cmp_ge_u32_e64 s[12:13], v217, s57
	s_bcnt1_i32_b64 s89, s[8:9]
	s_bcnt1_i32_b64 s61, s[12:13]
	s_add_u32 s89, s89, s61
	s_cmp_ge_u32 s89, s91
	s_cselect_b32 s33, s57, s33
	s_or_b32 s57, s33, 0x40000
	v_cmp_ge_u32_e64 s[8:9], v216, s57
	v_cmp_ge_u32_e64 s[12:13], v217, s57
	s_bcnt1_i32_b64 s89, s[8:9]
	s_bcnt1_i32_b64 s61, s[12:13]
	s_add_u32 s89, s89, s61
	s_cmp_ge_u32 s89, s91
	s_cselect_b32 s33, s57, s33
	s_or_b32 s57, s33, 0x20000
	v_cmp_ge_u32_e64 s[8:9], v216, s57
	v_cmp_ge_u32_e64 s[12:13], v217, s57
	s_bcnt1_i32_b64 s89, s[8:9]
	s_bcnt1_i32_b64 s61, s[12:13]
	s_add_u32 s89, s89, s61
	s_cmp_ge_u32 s89, s91
	s_cselect_b32 s33, s57, s33
	s_or_b32 s57, s33, 0x10000
	v_cmp_ge_u32_e64 s[8:9], v216, s57
	v_cmp_ge_u32_e64 s[12:13], v217, s57
	s_bcnt1_i32_b64 s89, s[8:9]
	s_bcnt1_i32_b64 s61, s[12:13]
	s_add_u32 s89, s89, s61
	s_cmp_ge_u32 s89, s91
	s_cselect_b32 s33, s57, s33
	s_or_b32 s57, s33, 0x8000
	v_cmp_ge_u32_e64 s[8:9], v216, s57
	v_cmp_ge_u32_e64 s[12:13], v217, s57
	s_bcnt1_i32_b64 s89, s[8:9]
	s_bcnt1_i32_b64 s61, s[12:13]
	s_add_u32 s89, s89, s61
	s_cmp_ge_u32 s89, s91
	s_cselect_b32 s33, s57, s33
	s_or_b32 s57, s33, 0x4000
	v_cmp_ge_u32_e64 s[8:9], v216, s57
	v_cmp_ge_u32_e64 s[12:13], v217, s57
	s_bcnt1_i32_b64 s89, s[8:9]
	s_bcnt1_i32_b64 s61, s[12:13]
	s_add_u32 s89, s89, s61
	s_cmp_ge_u32 s89, s91
	s_cselect_b32 s33, s57, s33
	s_or_b32 s57, s33, 0x2000
	v_cmp_ge_u32_e64 s[8:9], v216, s57
	v_cmp_ge_u32_e64 s[12:13], v217, s57
	s_bcnt1_i32_b64 s89, s[8:9]
	s_bcnt1_i32_b64 s61, s[12:13]
	s_add_u32 s89, s89, s61
	s_cmp_ge_u32 s89, s91
	s_cselect_b32 s33, s57, s33
	s_or_b32 s57, s33, 0x1000
	v_cmp_ge_u32_e64 s[8:9], v216, s57
	v_cmp_ge_u32_e64 s[12:13], v217, s57
	s_bcnt1_i32_b64 s89, s[8:9]
	s_bcnt1_i32_b64 s61, s[12:13]
	s_add_u32 s89, s89, s61
	s_cmp_ge_u32 s89, s91
	s_cselect_b32 s33, s57, s33
	s_or_b32 s57, s33, 0x800
	v_cmp_ge_u32_e64 s[8:9], v216, s57
	v_cmp_ge_u32_e64 s[12:13], v217, s57
	s_bcnt1_i32_b64 s89, s[8:9]
	s_bcnt1_i32_b64 s61, s[12:13]
	s_add_u32 s89, s89, s61
	s_cmp_ge_u32 s89, s91
	s_cselect_b32 s33, s57, s33
	s_or_b32 s57, s33, 0x400
	v_cmp_ge_u32_e64 s[8:9], v216, s57
	v_cmp_ge_u32_e64 s[12:13], v217, s57
	s_bcnt1_i32_b64 s89, s[8:9]
	s_bcnt1_i32_b64 s61, s[12:13]
	s_add_u32 s89, s89, s61
	s_cmp_ge_u32 s89, s91
	s_cselect_b32 s33, s57, s33
	s_or_b32 s57, s33, 0x200
	v_cmp_ge_u32_e64 s[8:9], v216, s57
	v_cmp_ge_u32_e64 s[12:13], v217, s57
	s_bcnt1_i32_b64 s89, s[8:9]
	s_bcnt1_i32_b64 s61, s[12:13]
	s_add_u32 s89, s89, s61
	s_cmp_ge_u32 s89, s91
	s_cselect_b32 s33, s57, s33
	s_or_b32 s57, s33, 0x100
	v_cmp_ge_u32_e64 s[8:9], v216, s57
	v_cmp_ge_u32_e64 s[12:13], v217, s57
	s_bcnt1_i32_b64 s89, s[8:9]
	s_bcnt1_i32_b64 s61, s[12:13]
	s_add_u32 s89, s89, s61
	s_cmp_ge_u32 s89, s91
	s_cselect_b32 s33, s57, s33
	s_or_b32 s57, s33, 0x80
	v_cmp_ge_u32_e64 s[8:9], v216, s57
	v_cmp_ge_u32_e64 s[12:13], v217, s57
	s_bcnt1_i32_b64 s89, s[8:9]
	s_bcnt1_i32_b64 s61, s[12:13]
	s_add_u32 s89, s89, s61
	s_cmp_ge_u32 s89, s91
	s_cselect_b32 s33, s57, s33
	s_or_b32 s57, s33, 0x40
	v_cmp_ge_u32_e64 s[8:9], v216, s57
	v_cmp_ge_u32_e64 s[12:13], v217, s57
	s_bcnt1_i32_b64 s89, s[8:9]
	s_bcnt1_i32_b64 s61, s[12:13]
	s_add_u32 s89, s89, s61
	s_cmp_ge_u32 s89, s91
	s_cselect_b32 s33, s57, s33
	s_or_b32 s57, s33, 0x20
	v_cmp_ge_u32_e64 s[8:9], v216, s57
	v_cmp_ge_u32_e64 s[12:13], v217, s57
	s_bcnt1_i32_b64 s89, s[8:9]
	s_bcnt1_i32_b64 s61, s[12:13]
	s_add_u32 s89, s89, s61
	s_cmp_ge_u32 s89, s91
	s_cselect_b32 s33, s57, s33
	s_or_b32 s57, s33, 0x10
	v_cmp_ge_u32_e64 s[8:9], v216, s57
	v_cmp_ge_u32_e64 s[12:13], v217, s57
	s_bcnt1_i32_b64 s89, s[8:9]
	s_bcnt1_i32_b64 s61, s[12:13]
	s_add_u32 s89, s89, s61
	s_cmp_ge_u32 s89, s91
	s_cselect_b32 s33, s57, s33
	s_or_b32 s57, s33, 0x8
	v_cmp_ge_u32_e64 s[8:9], v216, s57
	v_cmp_ge_u32_e64 s[12:13], v217, s57
	s_bcnt1_i32_b64 s89, s[8:9]
	s_bcnt1_i32_b64 s61, s[12:13]
	s_add_u32 s89, s89, s61
	s_cmp_ge_u32 s89, s91
	s_cselect_b32 s33, s57, s33
	s_or_b32 s57, s33, 0x4
	v_cmp_ge_u32_e64 s[8:9], v216, s57
	v_cmp_ge_u32_e64 s[12:13], v217, s57
	s_bcnt1_i32_b64 s89, s[8:9]
	s_bcnt1_i32_b64 s61, s[12:13]
	s_add_u32 s89, s89, s61
	s_cmp_ge_u32 s89, s91
	s_cselect_b32 s33, s57, s33
	s_or_b32 s57, s33, 0x2
	v_cmp_ge_u32_e64 s[8:9], v216, s57
	v_cmp_ge_u32_e64 s[12:13], v217, s57
	s_bcnt1_i32_b64 s89, s[8:9]
	s_bcnt1_i32_b64 s61, s[12:13]
	s_add_u32 s89, s89, s61
	s_cmp_ge_u32 s89, s91
	s_cselect_b32 s33, s57, s33
	s_or_b32 s57, s33, 0x1
	v_cmp_ge_u32_e64 s[8:9], v216, s57
	v_cmp_ge_u32_e64 s[12:13], v217, s57
	s_bcnt1_i32_b64 s89, s[8:9]
	s_bcnt1_i32_b64 s61, s[12:13]
	s_add_u32 s89, s89, s61
	s_cmp_ge_u32 s89, s91
	s_cselect_b32 s33, s57, s33
	v_cmp_gt_u32_e64 s[8:9], v216, s33
	v_cmp_gt_u32_e64 s[12:13], v217, s33
	s_bcnt1_i32_b64 s89, s[8:9]
	s_bcnt1_i32_b64 s61, s[12:13]
	s_add_u32 s89, s89, s61
	s_sub_u32 s91, s91, s89
	v_cmp_eq_u32_e64 s[8:9], v216, s33
	v_cmp_eq_u32_e64 s[12:13], v217, s33
	s_bcnt1_i32_b64 s89, s[8:9]
	s_bcnt1_i32_b64 s61, s[12:13]
	s_add_u32 s89, s89, s61
	s_add_u32 s57, s33, 1
	s_cmp_eq_u32 s91, s89
	s_cselect_b32 s57, s33, s57
	s_cselect_b32 s60, 1, 0
	v_cmp_ge_u32_e64 s[8:9], v216, s57
	v_cmp_ge_u32_e64 s[12:13], v217, s57
	s_nop 1
	v_mbcnt_lo_u32_b32 v241, s8, 0
	v_mbcnt_hi_u32_b32 v241, s9, v241
	v_add_u32_e32 v241, s90, v241
	v_and_b32_e32 v241, 0xff, v241
	v_lshl_add_u32 v241, v241, 1, v246
	s_mov_b64 exec, s[8:9]
	ds_write_b16 v241, v224
	s_mov_b64 exec, -1
	s_bcnt1_i32_b64 s61, s[8:9]
	s_add_u32 s90, s90, s61
	v_mbcnt_lo_u32_b32 v241, s12, 0
	v_mbcnt_hi_u32_b32 v241, s13, v241
	v_add_u32_e32 v241, s90, v241
	v_and_b32_e32 v241, 0xff, v241
	v_lshl_add_u32 v241, v241, 1, v246
	s_mov_b64 exec, s[12:13]
	ds_write_b16 v241, v225
	s_mov_b64 exec, -1
	s_bcnt1_i32_b64 s61, s[12:13]
	s_add_u32 s90, s90, s61
	s_mov_b32 s92, 0
	s_cmp_lg_u32 s60, 0
	s_cbranch_scc1 .Lref_fin
	v_cmp_eq_u32_e64 s[8:9], v216, s33
	v_cmp_eq_u32_e64 s[12:13], v217, s33
	s_nop 1
	v_mbcnt_lo_u32_b32 v241, s8, 0
	v_mbcnt_hi_u32_b32 v241, s9, v241
	v_add_u32_e32 v241, s92, v241
	v_lshl_add_u32 v241, v241, 1, v244
	s_mov_b64 exec, s[8:9]
	ds_write_b16 v241, v224
	s_mov_b64 exec, -1
	s_bcnt1_i32_b64 s61, s[8:9]
	s_add_u32 s92, s92, s61
	v_mbcnt_lo_u32_b32 v241, s12, 0
	v_mbcnt_hi_u32_b32 v241, s13, v241
	v_add_u32_e32 v241, s92, v241
	v_lshl_add_u32 v241, v241, 1, v244
	s_mov_b64 exec, s[12:13]
	ds_write_b16 v241, v225
	s_mov_b64 exec, -1
	s_bcnt1_i32_b64 s61, s[12:13]
	s_add_u32 s92, s92, s61
.Lref_fin:
	v_mov_b32_e32 v241, s91
	v_mov_b32_e32 v242, s90
	v_mov_b32_e32 v243, s92
	s_mov_b64 exec, 1
	ds_write_b32 v232, v241 offset:4
	ds_write2_b32 v232, v242, v243 offset0:2 offset1:3
	s_mov_b64 exec, -1

.LBB0_975:
	s_or_b64 exec, exec, s[4:5]
	v_mov_b32_e32 v15, v202
	s_add_u32 s62, s28, 0x14000000
	s_waitcnt lgkmcnt(0)
	s_barrier
	s_nop 0
	s_nop 0
	s_nop 0
	s_nop 0
	s_nop 0
	s_nop 0
	s_nop 0
	s_nop 0
	s_nop 0
	s_nop 0
	s_nop 0
	s_nop 0
	s_nop 0
	s_nop 0
	s_nop 0
	s_nop 0
	s_nop 0
	s_nop 0
	s_nop 0
	s_nop 0
	s_nop 0
	s_nop 0
	s_nop 0
	s_nop 0
	s_nop 0
	s_nop 0
	s_nop 0
	s_nop 0
	s_nop 0
	s_nop 0
	s_nop 0
	s_nop 0
	s_nop 0
	s_nop 0
	s_nop 0
	s_nop 0
	s_nop 0
	s_nop 0
	s_nop 0
	s_nop 0
	s_nop 0
	s_nop 0
	s_nop 0
	s_nop 0
	s_nop 0
	s_nop 0
	s_nop 0
	s_nop 0
	s_nop 0
	s_nop 0
	s_nop 0
	s_nop 0
	s_nop 0
	s_addc_u32 s63, s29, 0
	v_readfirstlane_b32 s4, v15
	s_ashr_i32 s4, s4, 6
	s_and_b64 s[6:7], s[46:47], exec
	s_cselect_b32 s5, 8, 1
	v_cvt_f32_ubyte0_e32 v1, s5
	v_rcp_iflag_f32_e32 v1, v1
	s_add_i32 s8, s5, -1
	s_and_b64 s[6:7], s[46:47], exec
	s_cselect_b32 s24, 3, 0
	v_mul_f32_e32 v1, 0x4f7ffffe, v1
	v_cvt_u32_f32_e32 v1, v1
	s_sub_i32 s9, 0, s5
	s_abs_i32 s7, s30
	s_lshr_b32 s6, s2, s24
	v_readfirstlane_b32 s10, v1
	s_mul_i32 s9, s9, s10
	s_mul_hi_u32 s9, s10, s9
	s_add_i32 s10, s10, s9
	s_mul_hi_u32 s9, s7, s10
	s_mul_i32 s10, s9, s5
	s_sub_i32 s7, s7, s10
	s_lshl_b32 s6, s6, 3
	s_ashr_i32 s68, s30, 31
	s_add_i32 s10, s9, 1
	s_sub_i32 s11, s7, s5
	s_cmp_ge_u32 s7, s5
	s_cselect_b32 s9, s10, s9
	s_cselect_b32 s7, s11, s7
	s_add_i32 s10, s9, 1
	s_cmp_ge_u32 s7, s5
	s_cselect_b32 s7, s10, s9
	s_xor_b32 s7, s7, s68
	s_sub_i32 s7, s7, s68
	s_lshl_b32 s25, s7, 3
	s_abs_i32 s7, s25
	v_cvt_f32_u32_e32 v1, s7
	s_add_i32 s40, s4, s6
	s_sub_i32 s6, s25, s40
	s_and_b32 s41, s8, s2
	v_rcp_iflag_f32_e32 v1, v1
	s_add_i32 s8, s6, 0x1fff
	s_sub_i32 s6, 0xffffe001, s6
	s_xor_b32 s9, s8, s25
	v_mul_f32_e32 v1, 0x4f7ffffe, v1
	v_cvt_u32_f32_e32 v1, v1
	s_max_i32 s6, s8, s6
	s_sub_i32 s8, 0, s7
	s_ashr_i32 s9, s9, 31
	v_readfirstlane_b32 s10, v1
	s_mul_i32 s8, s8, s10
	s_mul_hi_u32 s8, s10, s8
	s_add_i32 s10, s10, s8
	s_mul_hi_u32 s8, s6, s10
	s_mul_i32 s10, s8, s7
	s_sub_i32 s6, s6, s10
	s_add_i32 s10, s8, 1
	s_sub_i32 s11, s6, s7
	s_cmp_ge_u32 s6, s7
	s_cselect_b32 s8, s10, s8
	s_cselect_b32 s6, s11, s6
	s_add_i32 s10, s8, 1
	s_cmp_ge_u32 s6, s7
	s_cselect_b32 s6, s10, s8
	s_sub_i32 s5, s5, s41
	s_xor_b32 s6, s6, s9
	s_add_i32 s5, s5, 15
	s_sub_i32 s42, s6, s9
	s_lshr_b32 s5, s5, s24
	s_mul_i32 s43, s42, s5
	s_cmp_lt_i32 s43, 1
	s_mov_b32 s9, 0
	s_cbranch_scc1 .LBB0_980
	s_lshl_b32 s5, s4, 14
	s_lshl_b32 s4, s4, 10
	s_add_i32 s47, s4, 0
	s_lshr_b32 s8, s41, 2
	s_add_i32 s46, s5, 0
	s_add_i32 s47, s47, 0x20000
	s_and_b32 s10, s41, 3
	s_lshl_b64 s[4:5], s[8:9], 13
	s_ashr_i32 s6, s40, 31
	s_add_u32 s4, s4, s40
	s_addc_u32 s5, s5, s6
	s_lshl_b64 s[6:7], s[4:5], 9
	v_and_b32_e32 v14, 63, v15
	s_add_u32 s6, s44, s6
	s_addc_u32 s7, s45, s7
	v_lshlrev_b32_e32 v42, 3, v14
	global_load_dwordx2 v[2:3], v42, s[6:7]
	v_and_b32_e32 v17, 15, v15
	v_bfe_u32 v4, v15, 4, 2
	v_bfe_u32 v6, v15, 2, 2
	v_and_b32_e32 v1, 7, v15
	v_lshlrev_b32_e32 v34, 3, v15
	v_mov_b32_e32 v7, 0x1000
	v_lshrrev_b32_e32 v9, 3, v15
	v_or_b32_e32 v12, 16, v17
	v_lshl_or_b32 v6, v4, 2, v6
	v_bfe_u32 v5, v15, 3, 1
	v_and_b32_e32 v10, 1, v15
	v_bitop3_b32 v13, v4, v1, 4 bitop3:0x36
	v_bitop3_b32 v16, v4, v15, 7 bitop3:0x78
	v_and_or_b32 v7, v34, 24, v7
	v_xor_b32_e32 v9, v9, v15
	v_mul_u32_u24_e32 v21, 0x40004, v14
	v_lshrrev_b32_e32 v22, 3, v12
	v_lshlrev_b32_e32 v24, 4, v6
	v_lshlrev_b32_e32 v6, 7, v6
	s_cmpk_gt_i32 s40, 0xff
	s_movk_i32 s6, 0x60
	v_lshlrev_b32_e32 v12, 7, v12
	v_xor_b32_e32 v23, v13, v5
	v_xor_b32_e32 v5, v16, v5
	v_and_or_b32 v9, v9, 6, v10
	v_or_b32_e32 v60, 0x10000, v21
	v_or_b32_e32 v61, 0x30002, v21
	v_xor_b32_e32 v10, v13, v22
	v_xor_b32_e32 v13, v16, v22
	v_or_b32_e32 v16, 0x800, v6
	v_or_b32_e32 v6, v6, v7
	s_cselect_b64 vcc, -1, 0
	v_lshlrev_b32_e32 v11, 6, v15
	s_waitcnt vmcnt(2)
	v_lshlrev_b32_e32 v52, 4, v9
	v_add_u32_e32 v9, s47, v42
	v_lshl_or_b32 v37, v10, 4, v12
	v_bitop3_b32 v10, v24, v16, s6 bitop3:0xce
	v_bitop3_b32 v39, v24, v6, s6 bitop3:0xce
	s_mul_hi_u32 s6, s4, 0x1200
	s_mulk_i32 s5, 0x1200
	s_mulk_i32 s4, 0x1200
	s_add_i32 s6, s6, s5
	v_mov_b32_e32 v43, 0
	s_add_u32 s4, s38, s4
	v_mov_b32_e32 v8, 0x60
	v_lshlrev_b32_e32 v19, 7, v17
	s_addc_u32 s5, s39, s6
	v_lshl_or_b32 v35, v23, 4, v19
	v_lshl_or_b32 v36, v5, 4, v19
	v_and_b32_e32 v5, 0x60, v24
	v_bitop3_b32 v19, v24, 64, v8 bitop3:0x6c
	v_bitop3_b32 v8, v24, 32, v8 bitop3:0x6c
	v_bfe_u32 v18, v15, 3, 3
	v_lshl_or_b32 v38, v13, 4, v12
	v_or_b32_e32 v12, v19, v16
	v_or_b32_e32 v13, v8, v16
	v_or_b32_e32 v41, v8, v6
	v_or_b32_e32 v8, v5, v16
	s_waitcnt vmcnt(1)
	v_or_b32_e32 v56, v6, v5
	v_lshlrev_b32_e32 v16, 3, v4
	v_and_b32_e32 v4, 48, v15
	v_mov_b32_e32 v5, v43
	v_lshlrev_b32_e32 v63, 6, v18
	v_bitop3_b32 v20, v18, v15, 7 bitop3:0x78
	v_or_b32_e32 v40, v19, v6
	v_add_u32_e32 v57, v10, v7
	v_add_u32_e32 v58, v12, v7
	v_add_u32_e32 v59, v13, v7
	v_add_u32_e32 v90, v8, v7
	v_add_u32_e32 v18, s47, v63
	v_mov_b32_e32 v19, v43
	v_lshlrev_b32_e32 v44, 4, v20
	v_mov_b32_e32 v45, v43
	s_mov_b32 m0, s46
	v_mov_b32_e32 v53, v43
	v_mov_b32_e32 v64, 9
	v_xor_b32_e32 v50, 16, v44
	v_mov_b32_e32 v51, v43
	v_xor_b32_e32 v48, 32, v44
	s_waitcnt vmcnt(0)
	v_cndmask_b32_e32 v2, v60, v2, vcc
	v_cndmask_b32_e32 v3, v61, v3, vcc
	ds_write_b64 v9, v[2:3]
	v_and_b32_e32 v2, 0xc0, v11
	v_lshlrev_b32_e32 v62, 1, v2
	v_lshl_or_b32 v2, s10, 9, v62
	v_mov_b32_e32 v3, v43
	v_lshl_add_u64 v[2:3], s[4:5], 0, v[2:3]
	s_lshl_b64 s[4:5], s[8:9], 22
	s_add_u32 s6, s80, s4
	v_lshl_add_u64 v[2:3], v[2:3], 0, v[4:5]
	s_addc_u32 s7, s81, s5
	global_load_dwordx4 v[10:13], v[2:3], off
	global_load_dwordx4 v[6:9], v[2:3], off offset:64
	s_waitcnt lgkmcnt(0)
	s_add_u32 s4, s37, s4
	ds_read_b128 v[30:33], v18
	ds_read_b128 v[22:25], v18 offset:16
	ds_read_b128 v[2:5], v18 offset:32
	ds_read_b128 v[26:29], v18 offset:48
	s_addc_u32 s5, s79, s5
	s_lshl_b32 s8, s10, 7
	s_add_u32 s4, s4, s8
	s_addc_u32 s5, s5, 0
	s_waitcnt lgkmcnt(3)
	v_lshlrev_b32_e32 v18, 9, v30
	s_add_u32 s6, s6, s8
	v_and_b32_e32 v18, 0x1fffe00, v18
	s_addc_u32 s7, s7, 0
	v_lshl_add_u64 v[20:21], s[4:5], 0, v[18:19]
	s_add_i32 s48, s46, 0x1000
	v_lshl_add_u64 v[20:21], v[20:21], 0, v[44:45]
	v_lshl_add_u64 v[18:19], s[6:7], 0, v[18:19]
	global_load_lds_dwordx4 v[20:21], off
	v_lshl_add_u64 v[18:19], v[18:19], 0, v[52:53]
	s_mov_b32 m0, s48
	s_add_i32 s49, s46, 0x400
	global_load_lds_dwordx4 v[18:19], off
	v_lshlrev_b32_sdwa v18, v64, v30 dst_sel:DWORD dst_unused:UNUSED_PAD src0_sel:DWORD src1_sel:WORD_1
	v_mov_b32_e32 v19, v43
	v_lshl_add_u64 v[20:21], s[4:5], 0, v[18:19]
	v_lshl_add_u64 v[20:21], v[20:21], 0, v[50:51]
	s_mov_b32 m0, s49
	v_lshl_add_u64 v[18:19], s[6:7], 0, v[18:19]
	s_add_i32 s50, s46, 0x1400
	global_load_lds_dwordx4 v[20:21], off
	v_lshl_add_u64 v[18:19], v[18:19], 0, v[52:53]
	s_mov_b32 m0, s50
	v_mov_b32_e32 v49, v43
	global_load_lds_dwordx4 v[18:19], off
	v_lshlrev_b32_e32 v18, 9, v31
	v_and_b32_e32 v18, 0x1fffe00, v18
	v_mov_b32_e32 v19, v43
	v_lshl_add_u64 v[20:21], s[4:5], 0, v[18:19]
	s_add_i32 s51, s46, 0x800
	v_lshl_add_u64 v[20:21], v[20:21], 0, v[48:49]
	s_mov_b32 m0, s51
	v_lshl_add_u64 v[18:19], s[6:7], 0, v[18:19]
	s_add_i32 s52, s46, 0x1800
	global_load_lds_dwordx4 v[20:21], off
	v_lshl_add_u64 v[18:19], v[18:19], 0, v[52:53]
	s_mov_b32 m0, s52
	v_xor_b32_e32 v46, 48, v44
	global_load_lds_dwordx4 v[18:19], off
	v_lshlrev_b32_sdwa v18, v64, v31 dst_sel:DWORD dst_unused:UNUSED_PAD src0_sel:DWORD src1_sel:WORD_1
	v_mov_b32_e32 v19, v43
	v_lshl_add_u64 v[20:21], s[4:5], 0, v[18:19]
	v_mov_b32_e32 v47, v43
	s_add_i32 s53, s46, 0xc00
	v_lshl_add_u64 v[20:21], v[20:21], 0, v[46:47]
	s_mov_b32 m0, s53
	v_lshl_add_u64 v[18:19], s[6:7], 0, v[18:19]
	s_add_i32 s54, s46, 0x1c00
	global_load_lds_dwordx4 v[20:21], off
	v_lshl_add_u64 v[18:19], v[18:19], 0, v[52:53]
	s_mov_b32 m0, s54
	v_cmp_gt_u32_e64 s[4:5], 4, v17
	global_load_lds_dwordx4 v[18:19], off
	v_and_b32_e32 v17, 0x80, v34
	v_bfe_u32 v15, v15, 5, 1
	v_or_b32_e32 v19, 32, v17
	v_or_b32_e32 v20, 64, v17
	v_or_b32_e32 v21, 0x60, v17
	v_or_b32_e32 v30, 6, v15
	v_or_b32_e32 v82, v17, v30
	v_or_b32_e32 v84, v19, v30
	v_or_b32_e32 v86, v20, v30
	v_or_b32_e32 v88, v21, v30
	v_or_b32_e32 v30, 10, v15
	v_or_b32_e32 v18, 2, v15
	v_or_b32_e32 v98, v17, v30
	v_or_b32_e32 v100, v19, v30
	v_or_b32_e32 v102, v20, v30
	v_or_b32_e32 v104, v21, v30
	v_or_b32_e32 v30, 14, v15
	v_or_b32_e32 v66, v17, v18
	v_or_b32_e32 v68, v19, v18
	v_or_b32_e32 v70, v20, v18
	v_or_b32_e32 v72, v21, v18
	v_or_b32_e32 v18, 4, v15
	v_or_b32_e32 v106, v17, v30
	v_or_b32_e32 v108, v19, v30
	v_or_b32_e32 v110, v20, v30
	v_or_b32_e32 v112, v21, v30
	v_or_b32_e32 v30, 18, v15
	v_or_b32_e32 v81, v17, v18
	v_or_b32_e32 v83, v19, v18
	v_or_b32_e32 v85, v20, v18
	v_or_b32_e32 v87, v21, v18
	v_or_b32_e32 v18, 8, v15
	v_or_b32_e32 v114, v17, v30
	v_or_b32_e32 v116, v19, v30
	v_or_b32_e32 v118, v20, v30
	v_or_b32_e32 v120, v21, v30
	v_or_b32_e32 v30, 22, v15
	v_lshl_add_u64 v[54:55], s[44:45], 0, v[42:43]
	v_or_b32_e32 v97, v17, v18
	v_or_b32_e32 v99, v19, v18
	v_or_b32_e32 v101, v20, v18
	v_or_b32_e32 v103, v21, v18
	v_or_b32_e32 v18, 12, v15
	v_or_b32_e32 v122, v17, v30
	v_or_b32_e32 v124, v19, v30
	v_or_b32_e32 v126, v20, v30
	v_or_b32_e32 v128, v21, v30
	v_or_b32_e32 v30, 26, v15
	s_abs_i32 s45, s42
	v_or_b32_e32 v105, v17, v18
	v_or_b32_e32 v107, v19, v18
	v_or_b32_e32 v109, v20, v18
	v_or_b32_e32 v111, v21, v18
	v_or_b32_e32 v18, 16, v15
	v_or_b32_e32 v130, v17, v30
	v_or_b32_e32 v132, v19, v30
	v_or_b32_e32 v134, v20, v30
	v_or_b32_e32 v136, v21, v30
	v_cvt_f32_u32_e32 v30, s45
	v_or_b32_e32 v113, v17, v18
	v_or_b32_e32 v115, v19, v18
	v_or_b32_e32 v117, v20, v18
	v_or_b32_e32 v119, v21, v18
	v_or_b32_e32 v18, 20, v15
	v_or_b32_e32 v121, v17, v18
	v_or_b32_e32 v123, v19, v18
	v_or_b32_e32 v125, v20, v18
	v_or_b32_e32 v127, v21, v18
	v_or_b32_e32 v18, 24, v15
	v_or_b32_e32 v65, v17, v15
	v_or_b32_e32 v67, v19, v15
	v_or_b32_e32 v69, v20, v15
	v_or_b32_e32 v71, v21, v15
	v_or_b32_e32 v129, v17, v18
	v_or_b32_e32 v131, v19, v18
	v_or_b32_e32 v133, v20, v18
	v_or_b32_e32 v135, v21, v18
	v_or_b32_e32 v18, 28, v15
	v_or_b32_e32 v15, 30, v15
	v_or_b32_e32 v137, v17, v18
	v_or_b32_e32 v138, v17, v15
	v_rcp_iflag_f32_e32 v17, v30
	s_sub_i32 s8, 0, s45
	s_add_i32 s44, s46, 0x2000
	v_lshlrev_b32_e32 v1, 2, v14
	v_mul_f32_e32 v17, 0x4f7ffffe, v17
	v_cvt_u32_f32_e32 v17, v17
	s_waitcnt vmcnt(0)
	v_cndmask_b32_e64 v9, 0, v9, s[4:5]
	v_cndmask_b32_e64 v8, 0, v8, s[4:5]
	v_cndmask_b32_e64 v7, 0, v7, s[4:5]
	v_readfirstlane_b32 s10, v17
	s_mul_i32 s8, s8, s10
	s_mul_hi_u32 s8, s10, s8
	v_cndmask_b32_e64 v6, 0, v6, s[4:5]
	v_cndmask_b32_e64 v13, 0, v13, s[4:5]
	v_cndmask_b32_e64 v12, 0, v12, s[4:5]
	v_cndmask_b32_e64 v11, 0, v11, s[4:5]
	v_cndmask_b32_e64 v10, 0, v10, s[4:5]
	v_cmp_gt_u32_e64 s[6:7], 16, v14
	v_add_u32_e32 v73, s46, v56
	v_add_u32_e32 v74, s46, v90
	v_add_u32_e32 v75, s46, v41
	v_add_u32_e32 v76, s46, v59
	v_add_u32_e32 v77, s46, v40
	v_add_u32_e32 v78, s46, v58
	v_add_u32_e32 v79, s46, v39
	v_add_u32_e32 v80, s46, v57
	v_add_u32_e32 v89, s44, v56
	v_add_u32_e32 v90, s44, v90
	v_add_u32_e32 v91, s44, v41
	v_add_u32_e32 v92, s44, v59
	v_add_u32_e32 v93, s44, v40
	v_add_u32_e32 v94, s44, v58
	v_add_u32_e32 v95, s44, v39
	v_add_u32_e32 v96, s44, v57
	v_or_b32_e32 v139, v19, v18
	v_or_b32_e32 v140, v19, v15
	v_or_b32_e32 v141, v20, v18
	v_or_b32_e32 v142, v20, v15
	v_or_b32_e32 v143, v21, v18
	v_or_b32_e32 v144, v21, v15
	s_ashr_i32 s55, s42, 31
	s_add_i32 s56, s10, s8
	s_sub_i32 s57, 0, s42
	v_lshlrev_b32_e32 v56, 1, v16
	s_add_i32 s58, s46, 0x3000
	s_add_i32 s59, s46, 0x2400
	s_add_i32 s60, s46, 0x3400
	s_add_i32 s61, s46, 0x2800
	s_add_i32 s64, s46, 0x3800
	s_add_i32 s65, s46, 0x2c00
	s_add_i32 s66, s46, 0x3c00
	v_add_u32_e32 v145, s46, v36
	v_add_u32_e32 v149, s46, v35
	v_add_u32_e32 v151, s46, v38
	v_add_u32_e32 v153, s46, v37
	v_lshlrev_b32_e32 v58, 1, v14
	s_movk_i32 s67, 0x7fff
	s_mov_b32 s69, 0
	s_mov_b32 s70, 0
	s_branch .LBB0_978
